# c14 + rg_fused: spt loads hoisted above the MFMA k-loop, LDS A-fragment reads prefetched one m-step ahead (double-buffered quads)
# speedup vs baseline: 1.0039x; 1.0007x over previous
; #define LAS __attribute__((address_space(3)))
; #define RG_WLD(q, ksv) do { _Pragma("unroll") for (int n = 0; n < 4; ++n) \
;                 asm volatile("global_load_dwordx4 %0, %1, %2 offset:%3" : "=&v"(wq[q][n]) : "v"(wvo), "s"(wb[n]), "n"((ksv) * 1024 - 4096) : "memory"); } while (0)
; __device__ __forceinline__ void p_rg_fused(const Frame& F0, const bf16* URAW, int L, const float* cw, const float* cbias, const bf16* Wg, const float* ba, const float* bx, const float* spt,
;                                            bf16* LA, bf16* INP, float* HEND, float* PROD) {
;     ...
;             int Lq = F.lane; asm volatile("" : "+v"(Lq));
;             const int g = Lq >> 4, l15 = Lq & 15, w8 = F.wave;
;             bf16x8 wq[3][4];
;             const unsigned wvo = (unsigned)Lq * 16u;
;             const bf16* wtile0 = Wg + (size_t)((d * 8 + nb) * 2 + (w8 >> 2)) * 65536;
;             const bf16* wb[4];
; #pragma unroll
;             for (int n = 0; n < 4; ++n) wb[n] = wtile0 + (((w8 & 3) * 2 + (n & 1) + (n >> 1) * 8) * 8) * 512 + 2048;
;     ...
;             RG_WLD(0, 0); RG_WLD(1, 1);
;             f32x4 acc[8][4];
;             {
;                 float bn[4];
; #pragma unroll
;                 for (int n = 0; n < 4; ++n) { const int c = nb * 256 + 32 * w8 + 16 * (n & 1) + l15; bn[n] = -1.4426950408889634f * ((n >> 1) ? bx[d * D + c] : ba[d * D + c]); }
; #pragma unroll
;                 for (int m = 0; m < 8; ++m)
; #pragma unroll
;                     for (int n = 0; n < 4; ++n) acc[m][n] = (f32x4){bn[n], bn[n], bn[n], bn[n]};
; #pragma unroll
;                 for (int n = 0; n < 4; ++n) asm volatile("" : "+v"(acc[0][n]));
;             }
; #pragma unroll
;             for (int ks = 0; ks < 8; ++ks) {
;                 if (ks + 2 < 8) RG_WLD((ks + 2) % 3, ks + 2);
;                 if (ks <= 5) RG_WWAIT(ks % 3, 8); else if (ks == 6) RG_WWAIT(ks % 3, 4); else RG_WWAIT(ks % 3, 0);
; #pragma unroll
;                 for (int m = 0; m < 8; ++m) { const bf16x8 a = *(const LAS bf16x8*)(ut + (16 * m + l15) * RGF_PITCH + (32 * ks + 8 * g) * 2);
; #pragma unroll
;                     for (int n = 0; n < 4; ++n) acc[m][n] = __builtin_amdgcn_mfma_f32_16x16x32_bf16(a, wq[ks % 3][n], acc[m][n], 0, 0, 0); }
;     ...
;                 const float psp = spt[d * D + c];
.LBB0_856:
	v_and_b32_e32 v145, 15, v1
	v_or_b32_e32 v145, s35, v145
	v_add_u32_e32 v145, s57, v145
	v_lshlrev_b32_e32 v145, 2, v145
	s_lshl_b32 s0, s10, 13
	s_add_u32 s0, s86, s0
	s_addc_u32 s1, s87, 0
	global_load_dword v130, v145, s[0:1]
	global_load_dword v158, v145, s[0:1] offset:64
	s_lshl_b32 s0, s10, 4
	s_add_i32 s0, s2, s0
	s_ashr_i32 s1, s0, 31
	s_xor_b64 s[28:29], s[30:31], -1
	s_lshl_b64 s[0:1], s[0:1], 17
	s_add_u32 s0, s54, s0
	s_addc_u32 s1, s55, s1
	s_add_u32 s16, s0, 0x1000
	s_addc_u32 s17, s1, 0
	s_add_u32 s18, s0, 0x3000
	s_addc_u32 s19, s1, 0
	s_add_u32 s20, s0, 0x11000
	v_mov_b32_e32 v168, v1
	s_addc_u32 s21, s1, 0
	s_add_u32 s22, s0, 0x13000
	v_lshlrev_b32_e32 v50, 4, v168
	global_load_dwordx4 v[2:5], v50, s[16:17] offset:0xfffffffffffff000
	s_addc_u32 s23, s1, 0
	global_load_dwordx4 v[6:9], v50, s[18:19] offset:0xfffffffffffff000
	s_lshl_b32 s38, s10, 11
	global_load_dwordx4 v[10:13], v50, s[20:21] offset:0xfffffffffffff000
	v_and_b32_e32 v144, 15, v168
	s_add_i32 s0, s38, s60
	global_load_dwordx4 v[14:17], v50, s[22:23] offset:0xfffffffffffff000
	v_or_b32_e32 v34, s0, v144
	s_add_i32 s0, s38, s73
	global_load_dwordx4 v[18:21], v50, s[16:17] offset:0xfffffffffffff400
	v_or_b32_e32 v38, s0, v144
	global_load_dwordx4 v[22:25], v50, s[18:19] offset:0xfffffffffffff400
	v_ashrrev_i32_e32 v35, 31, v34
	v_ashrrev_i32_e32 v39, 31, v38
	global_load_dwordx4 v[26:29], v50, s[20:21] offset:0xfffffffffffff400
	v_lshlrev_b64 v[34:35], 2, v[34:35]
	v_lshlrev_b64 v[38:39], 2, v[38:39]
	global_load_dwordx4 v[30:33], v50, s[22:23] offset:0xfffffffffffff400
	v_lshl_add_u64 v[36:37], s[48:49], 0, v[34:35]
	v_lshl_add_u64 v[40:41], s[48:49], 0, v[38:39]
	v_lshl_add_u64 v[34:35], s[50:51], 0, v[34:35]
	global_load_dword v42, v[36:37], off
	s_nop 0
	global_load_dword v40, v[40:41], off
	v_lshl_add_u64 v[36:37], s[50:51], 0, v[38:39]
	global_load_dword v34, v[34:35], off
	s_nop 0
	global_load_dword v35, v[36:37], off
	v_and_b32_e32 v36, -16, v168
	v_mul_u32_u24_e32 v37, 0x210, v144
	v_add3_u32 v70, 0, v36, v37
	s_waitcnt vmcnt(3)
	v_mul_f32_e32 v52, 0xbfb8aa3b, v42
	s_waitcnt vmcnt(2)
	v_mul_f32_e32 v56, 0xbfb8aa3b, v40
	s_waitcnt vmcnt(1)
	v_mul_f32_e32 v60, 0xbfb8aa3b, v34
	s_waitcnt vmcnt(0)
	v_mul_f32_e32 v64, 0xbfb8aa3b, v35
	v_mov_b32_e32 v54, v52
	v_mov_b32_e32 v55, v52
	v_mov_b32_e32 v58, v56
	v_mov_b32_e32 v59, v56
	v_mov_b32_e32 v62, v60
	v_mov_b32_e32 v63, v60
	v_mov_b32_e32 v66, v64
	v_mov_b32_e32 v67, v64
	v_mov_b32_e32 v53, v52
	v_mov_b32_e32 v57, v56
	v_mov_b32_e32 v61, v60
	v_mov_b32_e32 v65, v64
	v_mov_b64_e32 v[74:75], v[54:55]
	v_mov_b64_e32 v[78:79], v[58:59]
	v_mov_b64_e32 v[82:83], v[62:63]
	v_mov_b64_e32 v[86:87], v[66:67]
	v_mov_b64_e32 v[72:73], v[52:53]
	v_mov_b64_e32 v[76:77], v[56:57]
	v_mov_b64_e32 v[80:81], v[60:61]
	v_mov_b64_e32 v[84:85], v[64:65]
	global_load_dwordx4 v[34:37], v50, s[16:17] offset:0xfffffffffffff800
	global_load_dwordx4 v[38:41], v50, s[18:19] offset:0xfffffffffffff800
	global_load_dwordx4 v[42:45], v50, s[20:21] offset:0xfffffffffffff800
	global_load_dwordx4 v[46:49], v50, s[22:23] offset:0xfffffffffffff800
	s_waitcnt vmcnt(8)
	ds_read_b128 v[88:91], v70
	ds_read_b128 v[92:95], v70 offset:8448
	ds_read_b128 v[104:107], v70 offset:16896
	ds_read_b128 v[108:111], v70 offset:25344
	ds_read_b128 v[140:143], v70 offset:33792
	ds_read_b128 v[146:149], v70 offset:42240
	ds_read_b128 v[164:167], v70 offset:50688
	ds_read_b128 v[186:189], v70 offset:59136
	s_waitcnt lgkmcnt(7)
	v_mfma_f32_16x16x32_bf16 v[72:75], v[88:91], v[2:5], v[72:75]
	v_mfma_f32_16x16x32_bf16 v[76:79], v[88:91], v[6:9], v[76:79]
	v_mfma_f32_16x16x32_bf16 v[80:83], v[88:91], v[10:13], v[80:83]
	v_mfma_f32_16x16x32_bf16 v[84:87], v[88:91], v[14:17], v[84:87]
	s_waitcnt lgkmcnt(6)
	v_mfma_f32_16x16x32_bf16 v[88:91], v[92:95], v[2:5], v[52:55]
	v_mfma_f32_16x16x32_bf16 v[96:99], v[92:95], v[6:9], v[56:59]
	v_mfma_f32_16x16x32_bf16 v[100:103], v[92:95], v[10:13], v[60:63]
	v_mfma_f32_16x16x32_bf16 v[92:95], v[92:95], v[14:17], v[64:67]
	s_waitcnt lgkmcnt(5)
	v_mfma_f32_16x16x32_bf16 v[112:115], v[104:107], v[2:5], v[52:55]
	v_mfma_f32_16x16x32_bf16 v[116:119], v[104:107], v[6:9], v[56:59]
	v_mfma_f32_16x16x32_bf16 v[120:123], v[104:107], v[10:13], v[60:63]
	v_mfma_f32_16x16x32_bf16 v[104:107], v[104:107], v[14:17], v[64:67]
	s_waitcnt lgkmcnt(4)
	v_mfma_f32_16x16x32_bf16 v[124:127], v[108:111], v[2:5], v[52:55]
	v_mfma_f32_16x16x32_bf16 v[132:135], v[108:111], v[6:9], v[56:59]
	v_mfma_f32_16x16x32_bf16 v[136:139], v[108:111], v[10:13], v[60:63]
	v_mfma_f32_16x16x32_bf16 v[108:111], v[108:111], v[14:17], v[64:67]
	s_waitcnt lgkmcnt(3)
	v_mfma_f32_16x16x32_bf16 v[150:153], v[140:143], v[2:5], v[52:55]
	v_mfma_f32_16x16x32_bf16 v[154:157], v[140:143], v[6:9], v[56:59]
	v_mfma_f32_16x16x32_bf16 v[170:173], v[140:143], v[10:13], v[60:63]
	v_mfma_f32_16x16x32_bf16 v[140:143], v[140:143], v[14:17], v[64:67]
	s_waitcnt lgkmcnt(2)
	v_mfma_f32_16x16x32_bf16 v[174:177], v[146:149], v[2:5], v[52:55]
	v_mfma_f32_16x16x32_bf16 v[178:181], v[146:149], v[6:9], v[56:59]
	v_mfma_f32_16x16x32_bf16 v[182:185], v[146:149], v[10:13], v[60:63]
	v_mfma_f32_16x16x32_bf16 v[146:149], v[146:149], v[14:17], v[64:67]
	s_waitcnt lgkmcnt(1)
	v_mfma_f32_16x16x32_bf16 v[206:209], v[164:167], v[2:5], v[52:55]
	v_mfma_f32_16x16x32_bf16 v[210:213], v[164:167], v[6:9], v[56:59]
	v_mfma_f32_16x16x32_bf16 v[214:217], v[164:167], v[10:13], v[60:63]
	v_mfma_f32_16x16x32_bf16 v[218:221], v[164:167], v[14:17], v[64:67]
	v_ashrrev_i32_e32 v164, 4, v168
	s_waitcnt lgkmcnt(0)
; #define LAS __attribute__((address_space(3)))
; #define RG_WLD(q, ksv) do { _Pragma("unroll") for (int n = 0; n < 4; ++n) \
;                 asm volatile("global_load_dwordx4 %0, %1, %2 offset:%3" : "=&v"(wq[q][n]) : "v"(wvo), "s"(wb[n]), "n"((ksv) * 1024 - 4096) : "memory"); } while (0)
; #define RG_WWAIT(q, cnt) asm volatile("s_waitcnt vmcnt(" #cnt ")" : "+v"(wq[q][0]), "+v"(wq[q][1]), "+v"(wq[q][2]), "+v"(wq[q][3]) :: "memory")
; __device__ __forceinline__ void p_rg_fused(const Frame& F0, const bf16* URAW, int L, const float* cw, const float* cbias, const bf16* Wg, const float* ba, const float* bx, const float* spt,
;                                            bf16* LA, bf16* INP, float* HEND, float* PROD) {
;     ...
;             for (int ks = 0; ks < 8; ++ks) {
;                 if (ks + 2 < 8) RG_WLD((ks + 2) % 3, ks + 2);
;                 if (ks <= 5) RG_WWAIT(ks % 3, 8); else if (ks == 6) RG_WWAIT(ks % 3, 4); else RG_WWAIT(ks % 3, 0);
; #pragma unroll
;                 for (int m = 0; m < 8; ++m) { const bf16x8 a = *(const LAS bf16x8*)(ut + (16 * m + l15) * RGF_PITCH + (32 * ks + 8 * g) * 2);
; #pragma unroll
;                     for (int n = 0; n < 4; ++n) acc[m][n] = __builtin_amdgcn_mfma_f32_16x16x32_bf16(a, wq[ks % 3][n], acc[m][n], 0, 0, 0); }
;                 __builtin_amdgcn_sched_barrier(0);
	ds_read_b128 v[222:225], v70 offset:64
	v_mfma_f32_16x16x32_bf16 v[52:55], v[186:189], v[2:5], v[52:55]
	v_mfma_f32_16x16x32_bf16 v[56:59], v[186:189], v[6:9], v[56:59]
	v_mfma_f32_16x16x32_bf16 v[60:63], v[186:189], v[10:13], v[60:63]
	v_mfma_f32_16x16x32_bf16 v[64:67], v[186:189], v[14:17], v[64:67]
	global_load_dwordx4 v[2:5], v50, s[16:17] offset:0xfffffffffffffc00
	global_load_dwordx4 v[6:9], v50, s[18:19] offset:0xfffffffffffffc00
	global_load_dwordx4 v[10:13], v50, s[20:21] offset:0xfffffffffffffc00
	global_load_dwordx4 v[14:17], v50, s[22:23] offset:0xfffffffffffffc00
	s_waitcnt vmcnt(8)
	s_waitcnt lgkmcnt(0)
	ds_read_b128 v[236:239], v70 offset:8512
	v_mfma_f32_16x16x32_bf16 v[72:75], v[222:225], v[18:21], v[72:75]
	v_mfma_f32_16x16x32_bf16 v[76:79], v[222:225], v[22:25], v[76:79]
	v_mfma_f32_16x16x32_bf16 v[80:83], v[222:225], v[26:29], v[80:83]
	v_mfma_f32_16x16x32_bf16 v[84:87], v[222:225], v[30:33], v[84:87]
	s_waitcnt lgkmcnt(0)
	ds_read_b128 v[240:243], v70 offset:16960
	v_mfma_f32_16x16x32_bf16 v[88:91], v[236:239], v[18:21], v[88:91]
	v_mfma_f32_16x16x32_bf16 v[96:99], v[236:239], v[22:25], v[96:99]
	v_mfma_f32_16x16x32_bf16 v[100:103], v[236:239], v[26:29], v[100:103]
	v_mfma_f32_16x16x32_bf16 v[92:95], v[236:239], v[30:33], v[92:95]
	s_waitcnt lgkmcnt(0)
	ds_read_b128 v[222:225], v70 offset:25408
	v_mfma_f32_16x16x32_bf16 v[112:115], v[240:243], v[18:21], v[112:115]
	v_mfma_f32_16x16x32_bf16 v[116:119], v[240:243], v[22:25], v[116:119]
	v_mfma_f32_16x16x32_bf16 v[120:123], v[240:243], v[26:29], v[120:123]
	v_mfma_f32_16x16x32_bf16 v[104:107], v[240:243], v[30:33], v[104:107]
	s_waitcnt lgkmcnt(0)
	ds_read_b128 v[236:239], v70 offset:33856
	v_mfma_f32_16x16x32_bf16 v[124:127], v[222:225], v[18:21], v[124:127]
	v_mfma_f32_16x16x32_bf16 v[132:135], v[222:225], v[22:25], v[132:135]
	v_mfma_f32_16x16x32_bf16 v[136:139], v[222:225], v[26:29], v[136:139]
	v_mfma_f32_16x16x32_bf16 v[108:111], v[222:225], v[30:33], v[108:111]
	s_waitcnt lgkmcnt(0)
	ds_read_b128 v[240:243], v70 offset:42304
	v_mfma_f32_16x16x32_bf16 v[150:153], v[236:239], v[18:21], v[150:153]
	v_mfma_f32_16x16x32_bf16 v[154:157], v[236:239], v[22:25], v[154:157]
	v_mfma_f32_16x16x32_bf16 v[170:173], v[236:239], v[26:29], v[170:173]
	v_mfma_f32_16x16x32_bf16 v[140:143], v[236:239], v[30:33], v[140:143]
	s_waitcnt lgkmcnt(0)
	ds_read_b128 v[222:225], v70 offset:50752
	v_mfma_f32_16x16x32_bf16 v[174:177], v[240:243], v[18:21], v[174:177]
	v_mfma_f32_16x16x32_bf16 v[178:181], v[240:243], v[22:25], v[178:181]
	v_mfma_f32_16x16x32_bf16 v[182:185], v[240:243], v[26:29], v[182:185]
	v_mfma_f32_16x16x32_bf16 v[146:149], v[240:243], v[30:33], v[146:149]
	s_waitcnt lgkmcnt(0)
	ds_read_b128 v[236:239], v70 offset:59200
	v_mfma_f32_16x16x32_bf16 v[206:209], v[222:225], v[18:21], v[206:209]
	v_mfma_f32_16x16x32_bf16 v[210:213], v[222:225], v[22:25], v[210:213]
	v_mfma_f32_16x16x32_bf16 v[214:217], v[222:225], v[26:29], v[214:217]
	v_mfma_f32_16x16x32_bf16 v[186:189], v[222:225], v[30:33], v[218:221]
	s_nop 2
	s_waitcnt lgkmcnt(0)
	ds_read_b128 v[240:243], v70 offset:128
	v_mfma_f32_16x16x32_bf16 v[52:55], v[236:239], v[18:21], v[52:55]
	v_mfma_f32_16x16x32_bf16 v[56:59], v[236:239], v[22:25], v[56:59]
	v_mfma_f32_16x16x32_bf16 v[60:63], v[236:239], v[26:29], v[60:63]
	v_mfma_f32_16x16x32_bf16 v[64:67], v[236:239], v[30:33], v[64:67]
	global_load_dwordx4 v[18:21], v50, s[16:17] offset:0
	global_load_dwordx4 v[22:25], v50, s[18:19] offset:0
	global_load_dwordx4 v[26:29], v50, s[20:21] offset:0
	global_load_dwordx4 v[30:33], v50, s[22:23] offset:0
	s_waitcnt vmcnt(8)
	s_waitcnt lgkmcnt(0)
	ds_read_b128 v[222:225], v70 offset:8576
	v_mfma_f32_16x16x32_bf16 v[72:75], v[240:243], v[34:37], v[72:75]
	v_mfma_f32_16x16x32_bf16 v[76:79], v[240:243], v[38:41], v[76:79]
	v_mfma_f32_16x16x32_bf16 v[80:83], v[240:243], v[42:45], v[80:83]
	v_mfma_f32_16x16x32_bf16 v[84:87], v[240:243], v[46:49], v[84:87]
	s_waitcnt lgkmcnt(0)
	ds_read_b128 v[236:239], v70 offset:17024
	v_mfma_f32_16x16x32_bf16 v[88:91], v[222:225], v[34:37], v[88:91]
	v_mfma_f32_16x16x32_bf16 v[96:99], v[222:225], v[38:41], v[96:99]
	v_mfma_f32_16x16x32_bf16 v[100:103], v[222:225], v[42:45], v[100:103]
	v_mfma_f32_16x16x32_bf16 v[92:95], v[222:225], v[46:49], v[92:95]
	s_waitcnt lgkmcnt(0)
	ds_read_b128 v[240:243], v70 offset:25472
	v_mfma_f32_16x16x32_bf16 v[112:115], v[236:239], v[34:37], v[112:115]
	v_mfma_f32_16x16x32_bf16 v[116:119], v[236:239], v[38:41], v[116:119]
	v_mfma_f32_16x16x32_bf16 v[120:123], v[236:239], v[42:45], v[120:123]
	v_mfma_f32_16x16x32_bf16 v[104:107], v[236:239], v[46:49], v[104:107]
	s_waitcnt lgkmcnt(0)
	ds_read_b128 v[222:225], v70 offset:33920
	v_mfma_f32_16x16x32_bf16 v[124:127], v[240:243], v[34:37], v[124:127]
	v_mfma_f32_16x16x32_bf16 v[132:135], v[240:243], v[38:41], v[132:135]
	v_mfma_f32_16x16x32_bf16 v[136:139], v[240:243], v[42:45], v[136:139]
	v_mfma_f32_16x16x32_bf16 v[108:111], v[240:243], v[46:49], v[108:111]
	s_waitcnt lgkmcnt(0)
	ds_read_b128 v[236:239], v70 offset:42368
	v_mfma_f32_16x16x32_bf16 v[150:153], v[222:225], v[34:37], v[150:153]
	v_mfma_f32_16x16x32_bf16 v[154:157], v[222:225], v[38:41], v[154:157]
	v_mfma_f32_16x16x32_bf16 v[170:173], v[222:225], v[42:45], v[170:173]
	v_mfma_f32_16x16x32_bf16 v[140:143], v[222:225], v[46:49], v[140:143]
	s_waitcnt lgkmcnt(0)
	ds_read_b128 v[240:243], v70 offset:50816
	v_mfma_f32_16x16x32_bf16 v[174:177], v[236:239], v[34:37], v[174:177]
	v_mfma_f32_16x16x32_bf16 v[178:181], v[236:239], v[38:41], v[178:181]
	v_mfma_f32_16x16x32_bf16 v[182:185], v[236:239], v[42:45], v[182:185]
	v_mfma_f32_16x16x32_bf16 v[146:149], v[236:239], v[46:49], v[146:149]
	s_waitcnt lgkmcnt(0)
; #define LAS __attribute__((address_space(3)))
; #define RG_WLD(q, ksv) do { _Pragma("unroll") for (int n = 0; n < 4; ++n) \
;                 asm volatile("global_load_dwordx4 %0, %1, %2 offset:%3" : "=&v"(wq[q][n]) : "v"(wvo), "s"(wb[n]), "n"((ksv) * 1024 - 4096) : "memory"); } while (0)
; #define RG_WWAIT(q, cnt) asm volatile("s_waitcnt vmcnt(" #cnt ")" : "+v"(wq[q][0]), "+v"(wq[q][1]), "+v"(wq[q][2]), "+v"(wq[q][3]) :: "memory")
; __device__ __forceinline__ void p_rg_fused(const Frame& F0, const bf16* URAW, int L, const float* cw, const float* cbias, const bf16* Wg, const float* ba, const float* bx, const float* spt,
;                                            bf16* LA, bf16* INP, float* HEND, float* PROD) {
;     ...
;             for (int ks = 0; ks < 8; ++ks) {
;                 if (ks + 2 < 8) RG_WLD((ks + 2) % 3, ks + 2);
;                 if (ks <= 5) RG_WWAIT(ks % 3, 8); else if (ks == 6) RG_WWAIT(ks % 3, 4); else RG_WWAIT(ks % 3, 0);
; #pragma unroll
;                 for (int m = 0; m < 8; ++m) { const bf16x8 a = *(const LAS bf16x8*)(ut + (16 * m + l15) * RGF_PITCH + (32 * ks + 8 * g) * 2);
; #pragma unroll
;                     for (int n = 0; n < 4; ++n) acc[m][n] = __builtin_amdgcn_mfma_f32_16x16x32_bf16(a, wq[ks % 3][n], acc[m][n], 0, 0, 0); }
;                 __builtin_amdgcn_sched_barrier(0);
	ds_read_b128 v[222:225], v70 offset:59264
	v_mfma_f32_16x16x32_bf16 v[206:209], v[240:243], v[34:37], v[206:209]
	v_mfma_f32_16x16x32_bf16 v[210:213], v[240:243], v[38:41], v[210:213]
	v_mfma_f32_16x16x32_bf16 v[214:217], v[240:243], v[42:45], v[214:217]
	v_mfma_f32_16x16x32_bf16 v[186:189], v[240:243], v[46:49], v[186:189]
	s_waitcnt lgkmcnt(0)
	ds_read_b128 v[236:239], v70 offset:192
	v_mfma_f32_16x16x32_bf16 v[52:55], v[222:225], v[34:37], v[52:55]
	v_mfma_f32_16x16x32_bf16 v[56:59], v[222:225], v[38:41], v[56:59]
	v_mfma_f32_16x16x32_bf16 v[60:63], v[222:225], v[42:45], v[60:63]
	v_mfma_f32_16x16x32_bf16 v[64:67], v[222:225], v[46:49], v[64:67]
	global_load_dwordx4 v[34:37], v50, s[16:17] offset:0x400
	global_load_dwordx4 v[38:41], v50, s[18:19] offset:0x400
	global_load_dwordx4 v[42:45], v50, s[20:21] offset:0x400
	global_load_dwordx4 v[46:49], v50, s[22:23] offset:0x400
	s_waitcnt vmcnt(8)
	s_waitcnt lgkmcnt(0)
	ds_read_b128 v[222:225], v70 offset:8640
	v_mfma_f32_16x16x32_bf16 v[72:75], v[236:239], v[2:5], v[72:75]
	v_mfma_f32_16x16x32_bf16 v[76:79], v[236:239], v[6:9], v[76:79]
	v_mfma_f32_16x16x32_bf16 v[80:83], v[236:239], v[10:13], v[80:83]
	v_mfma_f32_16x16x32_bf16 v[84:87], v[236:239], v[14:17], v[84:87]
	s_waitcnt lgkmcnt(0)
	ds_read_b128 v[240:243], v70 offset:17088
	v_mfma_f32_16x16x32_bf16 v[88:91], v[222:225], v[2:5], v[88:91]
	v_mfma_f32_16x16x32_bf16 v[96:99], v[222:225], v[6:9], v[96:99]
	v_mfma_f32_16x16x32_bf16 v[100:103], v[222:225], v[10:13], v[100:103]
	v_mfma_f32_16x16x32_bf16 v[92:95], v[222:225], v[14:17], v[92:95]
	s_waitcnt lgkmcnt(0)
	ds_read_b128 v[236:239], v70 offset:25536
	v_mfma_f32_16x16x32_bf16 v[112:115], v[240:243], v[2:5], v[112:115]
	v_mfma_f32_16x16x32_bf16 v[116:119], v[240:243], v[6:9], v[116:119]
	v_mfma_f32_16x16x32_bf16 v[120:123], v[240:243], v[10:13], v[120:123]
	v_mfma_f32_16x16x32_bf16 v[104:107], v[240:243], v[14:17], v[104:107]
	s_waitcnt lgkmcnt(0)
	ds_read_b128 v[222:225], v70 offset:33984
	v_mfma_f32_16x16x32_bf16 v[124:127], v[236:239], v[2:5], v[124:127]
	v_mfma_f32_16x16x32_bf16 v[132:135], v[236:239], v[6:9], v[132:135]
	v_mfma_f32_16x16x32_bf16 v[136:139], v[236:239], v[10:13], v[136:139]
	v_mfma_f32_16x16x32_bf16 v[108:111], v[236:239], v[14:17], v[108:111]
	s_waitcnt lgkmcnt(0)
	ds_read_b128 v[240:243], v70 offset:42432
	v_mfma_f32_16x16x32_bf16 v[150:153], v[222:225], v[2:5], v[150:153]
	v_mfma_f32_16x16x32_bf16 v[154:157], v[222:225], v[6:9], v[154:157]
	v_mfma_f32_16x16x32_bf16 v[170:173], v[222:225], v[10:13], v[170:173]
	v_mfma_f32_16x16x32_bf16 v[140:143], v[222:225], v[14:17], v[140:143]
	s_waitcnt lgkmcnt(0)
	ds_read_b128 v[236:239], v70 offset:50880
	v_mfma_f32_16x16x32_bf16 v[174:177], v[240:243], v[2:5], v[174:177]
	v_mfma_f32_16x16x32_bf16 v[178:181], v[240:243], v[6:9], v[178:181]
	v_mfma_f32_16x16x32_bf16 v[182:185], v[240:243], v[10:13], v[182:185]
	v_mfma_f32_16x16x32_bf16 v[146:149], v[240:243], v[14:17], v[146:149]
	s_waitcnt lgkmcnt(0)
	ds_read_b128 v[222:225], v70 offset:59328
	v_mfma_f32_16x16x32_bf16 v[206:209], v[236:239], v[2:5], v[206:209]
	v_mfma_f32_16x16x32_bf16 v[210:213], v[236:239], v[6:9], v[210:213]
	v_mfma_f32_16x16x32_bf16 v[214:217], v[236:239], v[10:13], v[214:217]
	v_mfma_f32_16x16x32_bf16 v[186:189], v[236:239], v[14:17], v[186:189]
	s_waitcnt lgkmcnt(0)
	ds_read_b128 v[240:243], v70 offset:256
	v_mfma_f32_16x16x32_bf16 v[52:55], v[222:225], v[2:5], v[52:55]
	v_mfma_f32_16x16x32_bf16 v[56:59], v[222:225], v[6:9], v[56:59]
	v_mfma_f32_16x16x32_bf16 v[60:63], v[222:225], v[10:13], v[60:63]
	v_mfma_f32_16x16x32_bf16 v[64:67], v[222:225], v[14:17], v[64:67]
	global_load_dwordx4 v[2:5], v50, s[16:17] offset:0x800
	global_load_dwordx4 v[6:9], v50, s[18:19] offset:0x800
	global_load_dwordx4 v[10:13], v50, s[20:21] offset:0x800
	global_load_dwordx4 v[14:17], v50, s[22:23] offset:0x800
	s_waitcnt vmcnt(8)
	s_waitcnt lgkmcnt(0)
	ds_read_b128 v[222:225], v70 offset:8704
	v_mfma_f32_16x16x32_bf16 v[72:75], v[240:243], v[18:21], v[72:75]
	v_mfma_f32_16x16x32_bf16 v[76:79], v[240:243], v[22:25], v[76:79]
	v_mfma_f32_16x16x32_bf16 v[80:83], v[240:243], v[26:29], v[80:83]
	v_mfma_f32_16x16x32_bf16 v[84:87], v[240:243], v[30:33], v[84:87]
	s_waitcnt lgkmcnt(0)
	ds_read_b128 v[244:247], v70 offset:17152
	v_mfma_f32_16x16x32_bf16 v[88:91], v[222:225], v[18:21], v[88:91]
	v_mfma_f32_16x16x32_bf16 v[96:99], v[222:225], v[22:25], v[96:99]
	v_mfma_f32_16x16x32_bf16 v[100:103], v[222:225], v[26:29], v[100:103]
	v_mfma_f32_16x16x32_bf16 v[92:95], v[222:225], v[30:33], v[92:95]
	s_waitcnt lgkmcnt(0)
	v_mfma_f32_16x16x32_bf16 v[236:239], v[244:247], v[26:29], v[120:123]
	s_nop 2
	ds_read_b128 v[120:123], v70 offset:25600
	v_mfma_f32_16x16x32_bf16 v[112:115], v[244:247], v[18:21], v[112:115]
	v_mfma_f32_16x16x32_bf16 v[116:119], v[244:247], v[22:25], v[116:119]
	v_mfma_f32_16x16x32_bf16 v[104:107], v[244:247], v[30:33], v[104:107]
	s_waitcnt lgkmcnt(0)
	ds_read_b128 v[222:225], v70 offset:34048
	v_mfma_f32_16x16x32_bf16 v[218:221], v[120:123], v[18:21], v[124:127]
	v_mfma_f32_16x16x32_bf16 v[240:243], v[120:123], v[22:25], v[132:135]
	v_mfma_f32_16x16x32_bf16 v[136:139], v[120:123], v[26:29], v[136:139]
	v_mfma_f32_16x16x32_bf16 v[108:111], v[120:123], v[30:33], v[108:111]
	s_waitcnt lgkmcnt(0)
	ds_read_b128 v[244:247], v70 offset:42496
	v_mfma_f32_16x16x32_bf16 v[150:153], v[222:225], v[18:21], v[150:153]
	v_mfma_f32_16x16x32_bf16 v[154:157], v[222:225], v[22:25], v[154:157]
	v_mfma_f32_16x16x32_bf16 v[170:173], v[222:225], v[26:29], v[170:173]
	v_mfma_f32_16x16x32_bf16 v[140:143], v[222:225], v[30:33], v[140:143]
	s_waitcnt lgkmcnt(0)
; #define LAS __attribute__((address_space(3)))
; #define RG_WLD(q, ksv) do { _Pragma("unroll") for (int n = 0; n < 4; ++n) \
;                 asm volatile("global_load_dwordx4 %0, %1, %2 offset:%3" : "=&v"(wq[q][n]) : "v"(wvo), "s"(wb[n]), "n"((ksv) * 1024 - 4096) : "memory"); } while (0)
; #define RG_WWAIT(q, cnt) asm volatile("s_waitcnt vmcnt(" #cnt ")" : "+v"(wq[q][0]), "+v"(wq[q][1]), "+v"(wq[q][2]), "+v"(wq[q][3]) :: "memory")
; __device__ __forceinline__ void p_rg_fused(const Frame& F0, const bf16* URAW, int L, const float* cw, const float* cbias, const bf16* Wg, const float* ba, const float* bx, const float* spt,
;                                            bf16* LA, bf16* INP, float* HEND, float* PROD) {
;     ...
;             for (int ks = 0; ks < 8; ++ks) {
;                 if (ks + 2 < 8) RG_WLD((ks + 2) % 3, ks + 2);
;                 if (ks <= 5) RG_WWAIT(ks % 3, 8); else if (ks == 6) RG_WWAIT(ks % 3, 4); else RG_WWAIT(ks % 3, 0);
; #pragma unroll
;                 for (int m = 0; m < 8; ++m) { const bf16x8 a = *(const LAS bf16x8*)(ut + (16 * m + l15) * RGF_PITCH + (32 * ks + 8 * g) * 2);
; #pragma unroll
;                     for (int n = 0; n < 4; ++n) acc[m][n] = __builtin_amdgcn_mfma_f32_16x16x32_bf16(a, wq[ks % 3][n], acc[m][n], 0, 0, 0); }
;                 __builtin_amdgcn_sched_barrier(0);
	ds_read_b128 v[124:127], v70 offset:50944
	v_mfma_f32_16x16x32_bf16 v[174:177], v[244:247], v[18:21], v[174:177]
	v_mfma_f32_16x16x32_bf16 v[178:181], v[244:247], v[22:25], v[178:181]
	v_mfma_f32_16x16x32_bf16 v[182:185], v[244:247], v[26:29], v[182:185]
	v_mfma_f32_16x16x32_bf16 v[146:149], v[244:247], v[30:33], v[146:149]
	s_waitcnt lgkmcnt(0)
	ds_read_b128 v[132:135], v70 offset:59392
	v_mfma_f32_16x16x32_bf16 v[206:209], v[124:127], v[18:21], v[206:209]
	v_mfma_f32_16x16x32_bf16 v[210:213], v[124:127], v[22:25], v[210:213]
	v_mfma_f32_16x16x32_bf16 v[214:217], v[124:127], v[26:29], v[214:217]
	v_mfma_f32_16x16x32_bf16 v[186:189], v[124:127], v[30:33], v[186:189]
	s_waitcnt lgkmcnt(0)
	ds_read_b128 v[222:225], v70 offset:320
	v_mfma_f32_16x16x32_bf16 v[18:21], v[132:135], v[18:21], v[52:55]
	v_mfma_f32_16x16x32_bf16 v[22:25], v[132:135], v[22:25], v[56:59]
	v_mfma_f32_16x16x32_bf16 v[26:29], v[132:135], v[26:29], v[60:63]
	v_mfma_f32_16x16x32_bf16 v[30:33], v[132:135], v[30:33], v[64:67]
	global_load_dwordx4 v[66:69], v50, s[16:17] offset:0xc00
	global_load_dwordx4 v[122:125], v50, s[18:19] offset:0xc00
	global_load_dwordx4 v[126:129], v50, s[20:21] offset:0xc00
	global_load_dwordx4 v[132:135], v50, s[22:23] offset:0xc00
	s_waitcnt vmcnt(8)
	s_waitcnt lgkmcnt(0)
	ds_read_b128 v[244:247], v70 offset:8768
	v_mfma_f32_16x16x32_bf16 v[54:57], v[222:225], v[34:37], v[72:75]
	s_nop 2
	v_mfma_f32_16x16x32_bf16 v[58:61], v[222:225], v[38:41], v[76:79]
	v_mfma_f32_16x16x32_bf16 v[62:65], v[222:225], v[42:45], v[80:83]
	s_waitcnt lgkmcnt(0)
	v_mfma_f32_16x16x32_bf16 v[76:79], v[244:247], v[34:37], v[88:91]
	s_nop 2
	ds_read_b128 v[88:91], v70 offset:17216
	v_mfma_f32_16x16x32_bf16 v[50:53], v[222:225], v[46:49], v[84:87]
	v_mfma_f32_16x16x32_bf16 v[80:83], v[244:247], v[38:41], v[96:99]
	v_mfma_f32_16x16x32_bf16 v[84:87], v[244:247], v[42:45], v[100:103]
	v_mfma_f32_16x16x32_bf16 v[72:75], v[244:247], v[46:49], v[92:95]
	s_waitcnt lgkmcnt(0)
	v_mfma_f32_16x16x32_bf16 v[92:95], v[88:91], v[34:37], v[112:115]
	v_mfma_f32_16x16x32_bf16 v[96:99], v[88:91], v[38:41], v[116:119]
	v_mfma_f32_16x16x32_bf16 v[100:103], v[88:91], v[42:45], v[236:239]
	v_mfma_f32_16x16x32_bf16 v[88:91], v[88:91], v[46:49], v[104:107]
	s_nop 2
	ds_read_b128 v[104:107], v70 offset:25664
	s_waitcnt lgkmcnt(0)
	ds_read_b128 v[222:225], v70 offset:34112
	v_mfma_f32_16x16x32_bf16 v[112:115], v[104:107], v[34:37], v[218:221]
	v_mfma_f32_16x16x32_bf16 v[116:119], v[104:107], v[38:41], v[240:243]
	v_mfma_f32_16x16x32_bf16 v[136:139], v[104:107], v[42:45], v[136:139]
	v_mfma_f32_16x16x32_bf16 v[104:107], v[104:107], v[46:49], v[108:111]
	s_nop 2
	s_waitcnt lgkmcnt(0)
	ds_read_b128 v[236:239], v70 offset:42560
	v_mfma_f32_16x16x32_bf16 v[150:153], v[222:225], v[34:37], v[150:153]
	v_mfma_f32_16x16x32_bf16 v[154:157], v[222:225], v[38:41], v[154:157]
	v_mfma_f32_16x16x32_bf16 v[170:173], v[222:225], v[42:45], v[170:173]
	v_mfma_f32_16x16x32_bf16 v[108:111], v[222:225], v[46:49], v[140:143]
	s_nop 2
	s_waitcnt lgkmcnt(0)
	ds_read_b128 v[218:221], v70 offset:51008
	v_mfma_f32_16x16x32_bf16 v[174:177], v[236:239], v[34:37], v[174:177]
	v_mfma_f32_16x16x32_bf16 v[178:181], v[236:239], v[38:41], v[178:181]
	v_mfma_f32_16x16x32_bf16 v[182:185], v[236:239], v[42:45], v[182:185]
	v_mfma_f32_16x16x32_bf16 v[140:143], v[236:239], v[46:49], v[146:149]
	s_nop 2
	s_waitcnt lgkmcnt(0)
	ds_read_b128 v[222:225], v70 offset:59456
	v_mfma_f32_16x16x32_bf16 v[206:209], v[218:221], v[34:37], v[206:209]
	v_mfma_f32_16x16x32_bf16 v[210:213], v[218:221], v[38:41], v[210:213]
	v_mfma_f32_16x16x32_bf16 v[214:217], v[218:221], v[42:45], v[214:217]
	v_mfma_f32_16x16x32_bf16 v[146:149], v[218:221], v[46:49], v[186:189]
	s_nop 2
	s_waitcnt lgkmcnt(0)
	ds_read_b128 v[236:239], v70 offset:384
	v_mfma_f32_16x16x32_bf16 v[18:21], v[222:225], v[34:37], v[18:21]
	v_mfma_f32_16x16x32_bf16 v[22:25], v[222:225], v[38:41], v[22:25]
	v_mfma_f32_16x16x32_bf16 v[26:29], v[222:225], v[42:45], v[26:29]
	v_mfma_f32_16x16x32_bf16 v[30:33], v[222:225], v[46:49], v[30:33]
	s_waitcnt vmcnt(4)
	s_waitcnt lgkmcnt(0)
	ds_read_b128 v[218:221], v70 offset:8832
	v_mfma_f32_16x16x32_bf16 v[38:41], v[236:239], v[2:5], v[54:57]
	v_mfma_f32_16x16x32_bf16 v[42:45], v[236:239], v[6:9], v[58:61]
	v_mfma_f32_16x16x32_bf16 v[46:49], v[236:239], v[10:13], v[62:65]
	s_nop 1
	ds_read_b128 v[58:61], v70 offset:17280
	v_mfma_f32_16x16x32_bf16 v[34:37], v[236:239], v[14:17], v[50:53]
	s_nop 2
	s_waitcnt lgkmcnt(0)
	ds_read_b128 v[222:225], v70 offset:25728
	v_mfma_f32_16x16x32_bf16 v[54:57], v[218:221], v[2:5], v[76:79]
	v_mfma_f32_16x16x32_bf16 v[76:79], v[218:221], v[6:9], v[80:83]
	v_mfma_f32_16x16x32_bf16 v[80:83], v[218:221], v[10:13], v[84:87]
	v_mfma_f32_16x16x32_bf16 v[50:53], v[218:221], v[14:17], v[72:75]
	v_mfma_f32_16x16x32_bf16 v[72:75], v[58:61], v[2:5], v[92:95]
	v_mfma_f32_16x16x32_bf16 v[84:87], v[58:61], v[6:9], v[96:99]
	v_mfma_f32_16x16x32_bf16 v[92:95], v[58:61], v[10:13], v[100:103]
	v_mfma_f32_16x16x32_bf16 v[88:91], v[58:61], v[14:17], v[88:91]
	s_waitcnt lgkmcnt(0)
	ds_read_b128 v[62:65], v70 offset:34176
	v_mfma_f32_16x16x32_bf16 v[96:99], v[222:225], v[2:5], v[112:115]
	v_mfma_f32_16x16x32_bf16 v[186:189], v[222:225], v[6:9], v[116:119]
	v_mfma_f32_16x16x32_bf16 v[218:221], v[222:225], v[10:13], v[136:139]
	v_mfma_f32_16x16x32_bf16 v[236:239], v[222:225], v[14:17], v[104:107]
	s_waitcnt lgkmcnt(0)
	ds_read_b128 v[100:103], v70 offset:42624
	v_mfma_f32_16x16x32_bf16 v[150:153], v[62:65], v[2:5], v[150:153]
	v_mfma_f32_16x16x32_bf16 v[154:157], v[62:65], v[6:9], v[154:157]
	v_mfma_f32_16x16x32_bf16 v[170:173], v[62:65], v[10:13], v[170:173]
	v_mfma_f32_16x16x32_bf16 v[240:243], v[62:65], v[14:17], v[108:111]
	s_waitcnt lgkmcnt(0)
; #define LAS __attribute__((address_space(3)))
; __device__ __forceinline__ float bf2f(bf16 b) { return __uint_as_float(((unsigned)b) << 16); }
; __device__ __forceinline__ float frcp_(float x) { return __builtin_amdgcn_rcpf(x); }
; __device__ __forceinline__ float fexp2_(float x) { return __builtin_amdgcn_exp2f(x); }
; #define RG_WWAIT(q, cnt) asm volatile("s_waitcnt vmcnt(" #cnt ")" : "+v"(wq[q][0]), "+v"(wq[q][1]), "+v"(wq[q][2]), "+v"(wq[q][3]) :: "memory")
; __device__ __forceinline__ void p_rg_fused(const Frame& F0, const bf16* URAW, int L, const float* cw, const float* cbias, const bf16* Wg, const float* ba, const float* bx, const float* spt,
;                                            bf16* LA, bf16* INP, float* HEND, float* PROD) {
;     ...
;             for (int ks = 0; ks < 8; ++ks) {
;                 if (ks + 2 < 8) RG_WLD((ks + 2) % 3, ks + 2);
;                 if (ks <= 5) RG_WWAIT(ks % 3, 8); else if (ks == 6) RG_WWAIT(ks % 3, 4); else RG_WWAIT(ks % 3, 0);
; #pragma unroll
;                 for (int m = 0; m < 8; ++m) { const bf16x8 a = *(const LAS bf16x8*)(ut + (16 * m + l15) * RGF_PITCH + (32 * ks + 8 * g) * 2);
; #pragma unroll
;                     for (int n = 0; n < 4; ++n) acc[m][n] = __builtin_amdgcn_mfma_f32_16x16x32_bf16(a, wq[ks % 3][n], acc[m][n], 0, 0, 0); }
;                 __builtin_amdgcn_sched_barrier(0);
;     ...
;                 const int cl = 32 * w8 + 16 * np + l15, c = nb * 256 + cl;
;                 const float psp = spt[d * D + c];
;                 float Lm[8], Hm[8];
; #pragma unroll
;                 for (int m = 0; m < 8; ++m) {
;                     float lr[4], xr[4], ea[4]; unsigned lwv[4], xwv[4];
;                     int gq = g; asm volatile("" : "+v"(gq));
;                     {
;                         f32x4 u4;
; #pragma unroll
;                         for (int e = 0; e < 4; ++e) u4[e] = bf2f(*(const LAS bf16*)(ut + (16 * m + 4 * gq + e) * RGF_PITCH + cl * 2));
;                         const f32x4 na = acc[m][np], nb2 = acc[m][2 + np]; f32x4 e1, e2;
; #pragma unroll
;                         for (int e = 0; e < 4; ++e) { e1[e] = fexp2_(fminf(na[e], 115.f)); e2[e] = fexp2_(fminf(nb2[e], 115.f)); }
;                         const f32x4 d1 = e1 + 1.0f, d2 = e2 + 1.0f, dp = d1 * d2; f32x4 rc;
; #pragma unroll
;                         for (int e = 0; e < 4; ++e) rc[e] = frcp_(dp[e]);
	ds_read_b128 v[104:107], v70 offset:51072
	v_mfma_f32_16x16x32_bf16 v[174:177], v[100:103], v[2:5], v[174:177]
	v_mfma_f32_16x16x32_bf16 v[178:181], v[100:103], v[6:9], v[178:181]
	v_mfma_f32_16x16x32_bf16 v[182:185], v[100:103], v[10:13], v[182:185]
	v_mfma_f32_16x16x32_bf16 v[244:247], v[100:103], v[14:17], v[140:143]
	s_waitcnt lgkmcnt(0)
	ds_read_b128 v[62:65], v70 offset:59520
	v_mfma_f32_16x16x32_bf16 v[206:209], v[104:107], v[2:5], v[206:209]
	v_mfma_f32_16x16x32_bf16 v[210:213], v[104:107], v[6:9], v[210:213]
	v_mfma_f32_16x16x32_bf16 v[214:217], v[104:107], v[10:13], v[214:217]
	v_mfma_f32_16x16x32_bf16 v[146:149], v[104:107], v[14:17], v[146:149]
	s_waitcnt lgkmcnt(0)
	ds_read_b128 v[100:103], v70 offset:448
	v_mfma_f32_16x16x32_bf16 v[2:5], v[62:65], v[2:5], v[18:21]
	v_mfma_f32_16x16x32_bf16 v[6:9], v[62:65], v[6:9], v[22:25]
	v_mfma_f32_16x16x32_bf16 v[194:197], v[62:65], v[10:13], v[26:29]
	v_mfma_f32_16x16x32_bf16 v[222:225], v[62:65], v[14:17], v[30:33]
	s_waitcnt vmcnt(0)
	s_waitcnt lgkmcnt(0)
	ds_read_b128 v[18:21], v70 offset:8896
	v_mfma_f32_16x16x32_bf16 v[140:143], v[100:103], v[66:69], v[38:41]
	v_mfma_f32_16x16x32_bf16 v[62:65], v[100:103], v[122:125], v[42:45]
	v_mfma_f32_16x16x32_bf16 v[136:139], v[100:103], v[126:129], v[46:49]
	v_mfma_f32_16x16x32_bf16 v[58:61], v[100:103], v[132:135], v[34:37]
	s_waitcnt lgkmcnt(0)
	ds_read_b128 v[14:17], v70 offset:17344
	v_mfma_f32_16x16x32_bf16 v[118:121], v[18:21], v[66:69], v[54:57]
	v_mfma_f32_16x16x32_bf16 v[54:57], v[18:21], v[122:125], v[76:79]
	v_mfma_f32_16x16x32_bf16 v[114:117], v[18:21], v[126:129], v[80:83]
	v_mfma_f32_16x16x32_bf16 v[50:53], v[18:21], v[132:135], v[50:53]
	s_waitcnt lgkmcnt(0)
	ds_read_b128 v[22:25], v70 offset:25792
	v_mfma_f32_16x16x32_bf16 v[110:113], v[14:17], v[66:69], v[72:75]
	v_mfma_f32_16x16x32_bf16 v[46:49], v[14:17], v[122:125], v[84:87]
	v_mfma_f32_16x16x32_bf16 v[106:109], v[14:17], v[126:129], v[92:95]
	v_mfma_f32_16x16x32_bf16 v[42:45], v[14:17], v[132:135], v[88:91]
	s_waitcnt lgkmcnt(0)
	ds_read_b128 v[18:21], v70 offset:34240
	v_mfma_f32_16x16x32_bf16 v[102:105], v[22:25], v[66:69], v[96:99]
	v_mfma_f32_16x16x32_bf16 v[38:41], v[22:25], v[122:125], v[186:189]
	v_mfma_f32_16x16x32_bf16 v[98:101], v[22:25], v[126:129], v[218:221]
	v_mfma_f32_16x16x32_bf16 v[34:37], v[22:25], v[132:135], v[236:239]
	s_waitcnt lgkmcnt(0)
	ds_read_b128 v[14:17], v70 offset:42688
	v_mfma_f32_16x16x32_bf16 v[94:97], v[18:21], v[66:69], v[150:153]
	v_mfma_f32_16x16x32_bf16 v[30:33], v[18:21], v[122:125], v[154:157]
	v_mfma_f32_16x16x32_bf16 v[90:93], v[18:21], v[126:129], v[170:173]
	v_mfma_f32_16x16x32_bf16 v[26:29], v[18:21], v[132:135], v[240:243]
	s_waitcnt lgkmcnt(0)
	ds_read_b128 v[218:221], v70 offset:51136
	v_mfma_f32_16x16x32_bf16 v[86:89], v[14:17], v[66:69], v[174:177]
	v_mfma_f32_16x16x32_bf16 v[22:25], v[14:17], v[122:125], v[178:181]
	v_mfma_f32_16x16x32_bf16 v[82:85], v[14:17], v[126:129], v[182:185]
	v_mfma_f32_16x16x32_bf16 v[18:21], v[14:17], v[132:135], v[244:247]
	s_waitcnt lgkmcnt(0)
	ds_read_b128 v[150:153], v70 offset:59584
	v_mfma_f32_16x16x32_bf16 v[78:81], v[218:221], v[66:69], v[206:209]
	v_mfma_f32_16x16x32_bf16 v[14:17], v[218:221], v[122:125], v[210:213]
	v_mfma_f32_16x16x32_bf16 v[74:77], v[218:221], v[126:129], v[214:217]
	v_mfma_f32_16x16x32_bf16 v[10:13], v[218:221], v[132:135], v[146:149]
	s_nop 2
	s_waitcnt lgkmcnt(0)
	v_mfma_f32_16x16x32_bf16 v[70:73], v[150:153], v[66:69], v[2:5]
	v_mfma_f32_16x16x32_bf16 v[6:9], v[150:153], v[122:125], v[6:9]
	v_mfma_f32_16x16x32_bf16 v[66:69], v[150:153], v[126:129], v[194:197]
	v_mfma_f32_16x16x32_bf16 v[2:5], v[150:153], v[132:135], v[222:225]
	v_or_b32_e32 v122, s35, v144
	v_and_b32_e32 v124, 1, v168
	v_mul_u32_u24_e32 v123, s83, v164
	v_cmp_eq_u32_e64 s[36:37], 0, v124
	v_lshl_add_u32 v123, v122, 1, v123
	v_add_u32_e32 v128, s57, v122
	v_lshlrev_b32_e32 v128, 2, v128
	v_mov_b32_e32 v125, 0x3020706
	v_mov_b32_e32 v129, 0x5040100
	v_cndmask_b32_e64 v125, v125, v129, s[36:37]
	v_lshl_or_b32 v126, v164, 2, v124
	v_and_b32_e32 v127, -2, v122
	v_lshlrev_b32_e32 v127, 1, v127
	v_lshl_add_u32 v126, v126, 12, v127
	v_add_u32_e32 v127, 0x2000, v126
	v_lshlrev_b32_e32 v177, 2, v168
	v_xor_b32_e32 v129, 64, v177
	v_xor_b32_e32 v177, 0x80, v177
	v_bfe_u32 v210, v168, 4, 1
	v_bfe_u32 v211, v168, 5, 1
	v_cmp_eq_u32_e64 s[40:41], s10, v210
	v_cmp_eq_u32_e64 s[38:39], s10, v211
	v_cmp_gt_u32_e64 s[42:43], 16, v168
	v_mov_b32_e32 v144, 0
	v_mov_b32_e32 v145, 0
	v_mov_b32_e32 v146, 0
	v_mov_b32_e32 v147, 0
	v_mov_b32_e32 v148, 0
	v_mov_b32_e32 v149, 0
	v_mov_b32_e32 v150, 0
	v_mov_b32_e32 v151, 0
	s_mov_b32 s20, 0x42e60000
	s_mov_b32 s21, 0xffff0000
	s_lshl_b32 s0, s10, 25
	s_add_u32 s16, s61, s0
	s_addc_u32 s17, s71, 0
	s_add_u32 s18, s65, s0
	s_addc_u32 s19, s72, 0
	ds_read_u16_d16_hi v144, v123 offset:0
	ds_read_u16_d16_hi v145, v123 offset:528
	ds_read_u16_d16_hi v146, v123 offset:1056
	ds_read_u16_d16_hi v147, v123 offset:1584
	ds_read_u16_d16_hi v148, v123 offset:8448
	ds_read_u16_d16_hi v149, v123 offset:8976
	ds_read_u16_d16_hi v150, v123 offset:9504
	ds_read_u16_d16_hi v151, v123 offset:10032
	v_min_f32_e32 v140, s20, v140
	v_min_f32_e32 v141, s20, v141
	v_min_f32_e32 v142, s20, v142
	v_min_f32_e32 v143, s20, v143
	v_min_f32_e32 v136, s20, v136
	v_min_f32_e32 v137, s20, v137
	v_min_f32_e32 v138, s20, v138
	v_min_f32_e32 v139, s20, v139
	v_exp_f32_e32 v140, v140
	v_exp_f32_e32 v141, v141
	v_exp_f32_e32 v142, v142
	v_exp_f32_e32 v143, v143
	v_exp_f32_e32 v136, v136
	v_exp_f32_e32 v137, v137
	v_exp_f32_e32 v138, v138
	v_exp_f32_e32 v139, v139
	v_pk_add_f32 v[140:141], v[140:141], 1.0 op_sel_hi:[1,0]
; #define LAS __attribute__((address_space(3)))
; __device__ __forceinline__ void p_rg_fused(const Frame& F0, const bf16* URAW, int L, const float* cw, const float* cbias, const bf16* Wg, const float* ba, const float* bx, const float* spt,
;                                            bf16* LA, bf16* INP, float* HEND, float* PROD) {
;     ...
;                 for (int m = 0; m < 8; ++m) {
;                     float lr[4], xr[4], ea[4]; unsigned lwv[4], xwv[4];
;                     int gq = g; asm volatile("" : "+v"(gq));
;                     {
;                         f32x4 u4;
; #pragma unroll
;                         for (int e = 0; e < 4; ++e) u4[e] = bf2f(*(const LAS bf16*)(ut + (16 * m + 4 * gq + e) * RGF_PITCH + cl * 2));
;                         const f32x4 na = acc[m][np], nb2 = acc[m][2 + np]; f32x4 e1, e2;
; #pragma unroll
;                         for (int e = 0; e < 4; ++e) { e1[e] = fexp2_(fminf(na[e], 115.f)); e2[e] = fexp2_(fminf(nb2[e], 115.f)); }
;                         const f32x4 d1 = e1 + 1.0f, d2 = e2 + 1.0f, dp = d1 * d2; f32x4 rc;
; #pragma unroll
;                         for (int e = 0; e < 4; ++e) rc[e] = frcp_(dp[e]);
;                         const f32x4 l4 = (d2 * rc) * psp, ig = d1 * rc;
;                         const unsigned lw01 = pk2(l4[0], l4[1]), lw23 = pk2(l4[2], l4[3]);
;                         lr[0] = bflo(lw01); lr[1] = bfhi(lw01); lr[2] = bflo(lw23); lr[3] = bfhi(lw23);
;                         f32x4 ea4, sq;
; #pragma unroll
;                         for (int e = 0; e < 4; ++e) { ea4[e] = fexp2_(lr[e]); ea[e] = ea4[e]; }
; #pragma unroll
;                         for (int e = 0; e < 4; ++e) sq[e] = fsqrt_(__builtin_fabsf(__builtin_fmaf(-ea4[e], ea4[e], 1.0f)));
;                         const f32x4 x4 = sq * ig * u4;
;                         const unsigned xw01 = pk2(x4[0], x4[1]), xw23 = pk2(x4[2], x4[3]);
;                         xr[0] = bflo(xw01); xr[1] = bfhi(xw01); xr[2] = bflo(xw23); xr[3] = bfhi(xw23);
;                         lwv[0] = lw01 & 0xffffu; lwv[1] = lw01 >> 16; lwv[2] = lw23 & 0xffffu; lwv[3] = lw23 >> 16;
;                         xwv[0] = xw01 & 0xffffu; xwv[1] = xw01 >> 16; xwv[2] = xw23 & 0xffffu; xwv[3] = xw23 >> 16; }
; #pragma unroll
;                     for (int ep = 0; ep < 2; ++ep) { const bool odd = (Lq & 1) != 0; const int tok = 16 * m + 4 * gq + 2 * ep + (odd ? 1 : 0);
	v_pk_add_f32 v[142:143], v[142:143], 1.0 op_sel_hi:[1,0]
	v_pk_add_f32 v[136:137], v[136:137], 1.0 op_sel_hi:[1,0]
	v_pk_add_f32 v[138:139], v[138:139], 1.0 op_sel_hi:[1,0]
	v_pk_mul_f32 v[178:179], v[140:141], v[136:137]
	v_pk_mul_f32 v[180:181], v[142:143], v[138:139]
	v_rcp_f32_e32 v178, v178
	v_rcp_f32_e32 v179, v179
	v_rcp_f32_e32 v180, v180
	v_rcp_f32_e32 v181, v181
	v_pk_mul_f32 v[136:137], v[136:137], v[178:179]
	v_pk_mul_f32 v[138:139], v[138:139], v[180:181]
	v_pk_mul_f32 v[140:141], v[140:141], v[178:179]
	v_pk_mul_f32 v[142:143], v[142:143], v[180:181]
	v_pk_mul_f32 v[136:137], v[136:137], v[130:131] op_sel_hi:[1,0]
	v_pk_mul_f32 v[138:139], v[138:139], v[130:131] op_sel_hi:[1,0]
	v_cvt_pk_bf16_f32 v178, v136, v137
	v_cvt_pk_bf16_f32 v179, v138, v139
	v_lshlrev_b32_e32 v136, 16, v178
	v_lshlrev_b32_e32 v137, 16, v179
	v_and_b32_e32 v138, s21, v178
	v_and_b32_e32 v139, s21, v179
	v_exp_f32_e32 v184, v136
	v_exp_f32_e32 v185, v138
	v_exp_f32_e32 v186, v137
	v_exp_f32_e32 v187, v139
	v_fma_f32 v180, -v184, v184, 1.0
	v_fma_f32 v181, -v185, v185, 1.0
	v_fma_f32 v182, -v186, v186, 1.0
	v_fma_f32 v183, -v187, v187, 1.0
	v_sqrt_f32_e64 v180, |v180|
	v_sqrt_f32_e64 v181, |v181|
	v_sqrt_f32_e64 v182, |v182|
	v_sqrt_f32_e64 v183, |v183|
	v_mov_b32_dpp v188, v178 quad_perm:[1,0,3,2] row_mask:0xf bank_mask:0xf bound_ctrl:1
	v_mov_b32_dpp v165, v179 quad_perm:[1,0,3,2] row_mask:0xf bank_mask:0xf bound_ctrl:1
	v_pk_mul_f32 v[180:181], v[180:181], v[140:141]
	v_pk_mul_f32 v[182:183], v[182:183], v[142:143]
	v_perm_b32 v206, v188, v178, v125
	v_perm_b32 v207, v165, v179, v125
	global_store_dword v126, v206, s[16:17] offset:0
	global_store_dword v127, v207, s[16:17] offset:0
	s_waitcnt lgkmcnt(4)
	v_pk_mul_f32 v[180:181], v[180:181], v[144:145]
	v_pk_mul_f32 v[182:183], v[182:183], v[146:147]
	v_pk_add_f32 v[136:137], v[136:137], v[138:139]
	v_cvt_pk_bf16_f32 v140, v180, v181
	v_cvt_pk_bf16_f32 v141, v182, v183
	v_add_f32_e32 v152, v136, v137
	v_lshlrev_b32_e32 v180, 16, v140
	v_mov_b32_dpp v188, v140 quad_perm:[1,0,3,2] row_mask:0xf bank_mask:0xf bound_ctrl:1
	v_and_b32_e32 v181, s21, v140
	v_mov_b32_dpp v165, v141 quad_perm:[1,0,3,2] row_mask:0xf bank_mask:0xf bound_ctrl:1
	v_lshlrev_b32_e32 v182, 16, v141
	v_and_b32_e32 v183, s21, v141
	v_perm_b32 v208, v188, v140, v125
	v_perm_b32 v209, v165, v141, v125
	global_store_dword v126, v208, s[18:19] offset:0
	global_store_dword v127, v209, s[18:19] offset:0
	s_add_u32 s16, s16, 0x10000
	s_addc_u32 s17, s17, 0
	s_add_u32 s18, s18, 0x10000
	s_addc_u32 s19, s19, 0
	v_fma_f32 v214, v180, v185, v181
	v_fma_f32 v215, v183, v186, v182
	v_fma_f32 v214, v214, v186, v182
	v_fma_f32 v215, v215, v185, v181
	v_fma_f32 v214, v214, v187, v183
	v_fma_f32 v215, v215, v184, v180
	ds_bpermute_b32 v210, v129, v152
	v_cndmask_b32_e64 v169, v215, v214, s[30:31]
	v_exp_f32_e32 v212, v152
	ds_bpermute_b32 v211, v129, v169
	ds_read_u16_d16_hi v144, v123 offset:16896
	ds_read_u16_d16_hi v145, v123 offset:17424
	ds_read_u16_d16_hi v146, v123 offset:17952
	ds_read_u16_d16_hi v147, v123 offset:18480
	v_min_f32_e32 v118, s20, v118
	v_min_f32_e32 v119, s20, v119
	v_min_f32_e32 v120, s20, v120
	v_min_f32_e32 v121, s20, v121
	v_min_f32_e32 v114, s20, v114
	v_min_f32_e32 v115, s20, v115
	v_min_f32_e32 v116, s20, v116
	v_min_f32_e32 v117, s20, v117
	v_exp_f32_e32 v118, v118
	v_exp_f32_e32 v119, v119
	v_exp_f32_e32 v120, v120
	v_exp_f32_e32 v121, v121
	v_exp_f32_e32 v114, v114
	v_exp_f32_e32 v115, v115
	v_exp_f32_e32 v116, v116
	v_exp_f32_e32 v117, v117
	v_pk_add_f32 v[118:119], v[118:119], 1.0 op_sel_hi:[1,0]
	v_pk_add_f32 v[120:121], v[120:121], 1.0 op_sel_hi:[1,0]
	v_pk_add_f32 v[114:115], v[114:115], 1.0 op_sel_hi:[1,0]
	v_pk_add_f32 v[116:117], v[116:117], 1.0 op_sel_hi:[1,0]
	v_pk_mul_f32 v[216:217], v[118:119], v[114:115]
	v_pk_mul_f32 v[218:219], v[120:121], v[116:117]
	v_rcp_f32_e32 v216, v216
	v_rcp_f32_e32 v217, v217
	v_rcp_f32_e32 v218, v218
	v_rcp_f32_e32 v219, v219
	v_pk_mul_f32 v[114:115], v[114:115], v[216:217]
	v_pk_mul_f32 v[116:117], v[116:117], v[218:219]
	v_pk_mul_f32 v[118:119], v[118:119], v[216:217]
	v_pk_mul_f32 v[120:121], v[120:121], v[218:219]
	v_pk_mul_f32 v[114:115], v[114:115], v[130:131] op_sel_hi:[1,0]
	v_pk_mul_f32 v[116:117], v[116:117], v[130:131] op_sel_hi:[1,0]
	v_cvt_pk_bf16_f32 v216, v114, v115
	v_cvt_pk_bf16_f32 v217, v116, v117
	v_lshlrev_b32_e32 v114, 16, v216
	v_lshlrev_b32_e32 v115, 16, v217
	v_and_b32_e32 v116, s21, v216
	v_and_b32_e32 v117, s21, v217
	v_exp_f32_e32 v222, v114
	v_exp_f32_e32 v223, v116
	v_exp_f32_e32 v224, v115
	v_exp_f32_e32 v225, v117
	s_waitcnt lgkmcnt(4)
; #define LAS __attribute__((address_space(3)))
; __device__ __forceinline__ void p_rg_fused(const Frame& F0, const bf16* URAW, int L, const float* cw, const float* cbias, const bf16* Wg, const float* ba, const float* bx, const float* spt,
;                                            bf16* LA, bf16* INP, float* HEND, float* PROD) {
;     ...
;                 for (int m = 0; m < 8; ++m) {
;                     float lr[4], xr[4], ea[4]; unsigned lwv[4], xwv[4];
;                     int gq = g; asm volatile("" : "+v"(gq));
;                     {
;                         f32x4 u4;
; #pragma unroll
;                         for (int e = 0; e < 4; ++e) u4[e] = bf2f(*(const LAS bf16*)(ut + (16 * m + 4 * gq + e) * RGF_PITCH + cl * 2));
;                         const f32x4 na = acc[m][np], nb2 = acc[m][2 + np]; f32x4 e1, e2;
; #pragma unroll
;                         for (int e = 0; e < 4; ++e) { e1[e] = fexp2_(fminf(na[e], 115.f)); e2[e] = fexp2_(fminf(nb2[e], 115.f)); }
;                         const f32x4 d1 = e1 + 1.0f, d2 = e2 + 1.0f, dp = d1 * d2; f32x4 rc;
; #pragma unroll
;                         for (int e = 0; e < 4; ++e) rc[e] = frcp_(dp[e]);
;                         const f32x4 l4 = (d2 * rc) * psp, ig = d1 * rc;
;                         const unsigned lw01 = pk2(l4[0], l4[1]), lw23 = pk2(l4[2], l4[3]);
;                         lr[0] = bflo(lw01); lr[1] = bfhi(lw01); lr[2] = bflo(lw23); lr[3] = bfhi(lw23);
;                         f32x4 ea4, sq;
; #pragma unroll
;                         for (int e = 0; e < 4; ++e) { ea4[e] = fexp2_(lr[e]); ea[e] = ea4[e]; }
; #pragma unroll
;                         for (int e = 0; e < 4; ++e) sq[e] = fsqrt_(__builtin_fabsf(__builtin_fmaf(-ea4[e], ea4[e], 1.0f)));
;                         const f32x4 x4 = sq * ig * u4;
;                         const unsigned xw01 = pk2(x4[0], x4[1]), xw23 = pk2(x4[2], x4[3]);
;                         xr[0] = bflo(xw01); xr[1] = bfhi(xw01); xr[2] = bflo(xw23); xr[3] = bfhi(xw23);
;                         lwv[0] = lw01 & 0xffffu; lwv[1] = lw01 >> 16; lwv[2] = lw23 & 0xffffu; lwv[3] = lw23 >> 16;
;                         xwv[0] = xw01 & 0xffffu; xwv[1] = xw01 >> 16; xwv[2] = xw23 & 0xffffu; xwv[3] = xw23 >> 16; }
; #pragma unroll
;                     for (int ep = 0; ep < 2; ++ep) { const bool odd = (Lq & 1) != 0; const int tok = 16 * m + 4 * gq + 2 * ep + (odd ? 1 : 0);
	v_exp_f32_e32 v213, v210
	v_fma_f32 v215, v211, v212, v169
	v_add_f32_e32 v152, v152, v210
	v_fma_f32 v214, v169, v213, v211
	v_cndmask_b32_e64 v169, v215, v214, s[40:41]
	ds_bpermute_b32 v210, v177, v152
	v_exp_f32_e32 v212, v152
	ds_bpermute_b32 v211, v177, v169
	v_fma_f32 v218, -v222, v222, 1.0
	v_fma_f32 v219, -v223, v223, 1.0
	v_fma_f32 v220, -v224, v224, 1.0
	v_fma_f32 v221, -v225, v225, 1.0
	v_sqrt_f32_e64 v218, |v218|
	v_sqrt_f32_e64 v219, |v219|
	v_sqrt_f32_e64 v220, |v220|
	v_sqrt_f32_e64 v221, |v221|
	v_mov_b32_dpp v166, v216 quad_perm:[1,0,3,2] row_mask:0xf bank_mask:0xf bound_ctrl:1
	v_mov_b32_dpp v167, v217 quad_perm:[1,0,3,2] row_mask:0xf bank_mask:0xf bound_ctrl:1
	v_pk_mul_f32 v[218:219], v[218:219], v[118:119]
	v_pk_mul_f32 v[220:221], v[220:221], v[120:121]
	v_perm_b32 v236, v166, v216, v125
	v_perm_b32 v237, v167, v217, v125
	global_store_dword v126, v236, s[16:17] offset:0
	global_store_dword v127, v237, s[16:17] offset:0
	v_pk_mul_f32 v[218:219], v[218:219], v[148:149]
	v_pk_mul_f32 v[220:221], v[220:221], v[150:151]
	v_pk_add_f32 v[114:115], v[114:115], v[116:117]
	v_cvt_pk_bf16_f32 v118, v218, v219
	v_cvt_pk_bf16_f32 v119, v220, v221
	v_add_f32_e32 v153, v114, v115
	v_lshlrev_b32_e32 v218, 16, v118
	v_mov_b32_dpp v166, v118 quad_perm:[1,0,3,2] row_mask:0xf bank_mask:0xf bound_ctrl:1
	v_and_b32_e32 v219, s21, v118
	v_mov_b32_dpp v167, v119 quad_perm:[1,0,3,2] row_mask:0xf bank_mask:0xf bound_ctrl:1
	v_lshlrev_b32_e32 v220, 16, v119
	v_and_b32_e32 v221, s21, v119
	v_perm_b32 v238, v166, v118, v125
	v_perm_b32 v239, v167, v119, v125
	global_store_dword v126, v238, s[18:19] offset:0
	global_store_dword v127, v239, s[18:19] offset:0
	s_add_u32 s16, s16, 0x10000
	s_addc_u32 s17, s17, 0
	s_add_u32 s18, s18, 0x10000
	s_addc_u32 s19, s19, 0
	v_fma_f32 v244, v218, v223, v219
	v_fma_f32 v245, v221, v224, v220
	v_fma_f32 v244, v244, v224, v220
	v_fma_f32 v245, v245, v223, v219
	v_fma_f32 v244, v244, v225, v221
	v_fma_f32 v245, v245, v222, v218
	ds_bpermute_b32 v240, v129, v153
	v_cndmask_b32_e64 v170, v245, v244, s[30:31]
	v_exp_f32_e32 v242, v153
	ds_bpermute_b32 v241, v129, v170
	s_waitcnt lgkmcnt(2)
	v_exp_f32_e32 v213, v210
	v_fma_f32 v215, v211, v212, v169
	v_add_f32_e32 v152, v152, v210
	v_fma_f32 v214, v169, v213, v211
	v_cndmask_b32_e64 v169, v215, v214, s[38:39]
	ds_read_u16_d16_hi v148, v123 offset:25344
	ds_read_u16_d16_hi v149, v123 offset:25872
	ds_read_u16_d16_hi v150, v123 offset:26400
	ds_read_u16_d16_hi v151, v123 offset:26928
	v_min_f32_e32 v110, s20, v110
	v_min_f32_e32 v111, s20, v111
	v_min_f32_e32 v112, s20, v112
	v_min_f32_e32 v113, s20, v113
	v_min_f32_e32 v106, s20, v106
	v_min_f32_e32 v107, s20, v107
	v_min_f32_e32 v108, s20, v108
	v_min_f32_e32 v109, s20, v109
	v_exp_f32_e32 v110, v110
	v_exp_f32_e32 v111, v111
	v_exp_f32_e32 v112, v112
	v_exp_f32_e32 v113, v113
	v_exp_f32_e32 v106, v106
	v_exp_f32_e32 v107, v107
	v_exp_f32_e32 v108, v108
	v_exp_f32_e32 v109, v109
	v_pk_add_f32 v[110:111], v[110:111], 1.0 op_sel_hi:[1,0]
	v_pk_add_f32 v[112:113], v[112:113], 1.0 op_sel_hi:[1,0]
	v_pk_add_f32 v[106:107], v[106:107], 1.0 op_sel_hi:[1,0]
	v_pk_add_f32 v[108:109], v[108:109], 1.0 op_sel_hi:[1,0]
	v_pk_mul_f32 v[178:179], v[110:111], v[106:107]
	v_pk_mul_f32 v[180:181], v[112:113], v[108:109]
	v_rcp_f32_e32 v178, v178
	v_rcp_f32_e32 v179, v179
	v_rcp_f32_e32 v180, v180
	v_rcp_f32_e32 v181, v181
	v_pk_mul_f32 v[106:107], v[106:107], v[178:179]
	v_pk_mul_f32 v[108:109], v[108:109], v[180:181]
	v_pk_mul_f32 v[110:111], v[110:111], v[178:179]
	v_pk_mul_f32 v[112:113], v[112:113], v[180:181]
	v_pk_mul_f32 v[106:107], v[106:107], v[130:131] op_sel_hi:[1,0]
	v_pk_mul_f32 v[108:109], v[108:109], v[130:131] op_sel_hi:[1,0]
	v_cvt_pk_bf16_f32 v178, v106, v107
	v_cvt_pk_bf16_f32 v179, v108, v109
	v_lshlrev_b32_e32 v106, 16, v178
	v_lshlrev_b32_e32 v107, 16, v179
	v_and_b32_e32 v108, s21, v178
	v_and_b32_e32 v109, s21, v179
	v_exp_f32_e32 v184, v106
	v_exp_f32_e32 v185, v108
	v_exp_f32_e32 v186, v107
	v_exp_f32_e32 v187, v109
	s_waitcnt lgkmcnt(4)
	v_exp_f32_e32 v243, v240
	v_fma_f32 v245, v241, v242, v170
	v_add_f32_e32 v153, v153, v240
	v_fma_f32 v244, v170, v243, v241
	v_cndmask_b32_e64 v170, v245, v244, s[40:41]
	ds_bpermute_b32 v240, v177, v153
	v_exp_f32_e32 v242, v153
	ds_bpermute_b32 v241, v177, v170
	v_fma_f32 v180, -v184, v184, 1.0
	v_fma_f32 v181, -v185, v185, 1.0
	v_fma_f32 v182, -v186, v186, 1.0
	v_fma_f32 v183, -v187, v187, 1.0
	v_sqrt_f32_e64 v180, |v180|
	v_sqrt_f32_e64 v181, |v181|
	v_sqrt_f32_e64 v182, |v182|
	v_sqrt_f32_e64 v183, |v183|
	v_mov_b32_dpp v188, v178 quad_perm:[1,0,3,2] row_mask:0xf bank_mask:0xf bound_ctrl:1
	v_mov_b32_dpp v165, v179 quad_perm:[1,0,3,2] row_mask:0xf bank_mask:0xf bound_ctrl:1
	v_pk_mul_f32 v[180:181], v[180:181], v[110:111]
	v_pk_mul_f32 v[182:183], v[182:183], v[112:113]
	v_perm_b32 v206, v188, v178, v125
	v_perm_b32 v207, v165, v179, v125
	global_store_dword v126, v206, s[16:17] offset:0
	global_store_dword v127, v207, s[16:17] offset:0
	v_pk_mul_f32 v[180:181], v[180:181], v[144:145]
	v_pk_mul_f32 v[182:183], v[182:183], v[146:147]
	v_pk_add_f32 v[106:107], v[106:107], v[108:109]
	v_cvt_pk_bf16_f32 v110, v180, v181
	v_cvt_pk_bf16_f32 v111, v182, v183
	v_add_f32_e32 v154, v106, v107
	v_lshlrev_b32_e32 v180, 16, v110
	v_mov_b32_dpp v188, v110 quad_perm:[1,0,3,2] row_mask:0xf bank_mask:0xf bound_ctrl:1
	v_and_b32_e32 v181, s21, v110
	v_mov_b32_dpp v165, v111 quad_perm:[1,0,3,2] row_mask:0xf bank_mask:0xf bound_ctrl:1
	v_lshlrev_b32_e32 v182, 16, v111
	v_and_b32_e32 v183, s21, v111
	v_perm_b32 v208, v188, v110, v125
	v_perm_b32 v209, v165, v111, v125
	global_store_dword v126, v208, s[18:19] offset:0
	global_store_dword v127, v209, s[18:19] offset:0
	s_add_u32 s16, s16, 0x10000
	s_addc_u32 s17, s17, 0
	s_add_u32 s18, s18, 0x10000
	s_addc_u32 s19, s19, 0
	v_fma_f32 v214, v180, v185, v181
	v_fma_f32 v215, v183, v186, v182
	v_fma_f32 v214, v214, v186, v182
	v_fma_f32 v215, v215, v185, v181
	v_fma_f32 v214, v214, v187, v183
	v_fma_f32 v215, v215, v184, v180
	ds_bpermute_b32 v210, v129, v154
	v_cndmask_b32_e64 v171, v215, v214, s[30:31]
	v_exp_f32_e32 v212, v154
	ds_bpermute_b32 v211, v129, v171
	s_waitcnt lgkmcnt(2)
; #define LAS __attribute__((address_space(3)))
; __device__ __forceinline__ void p_rg_fused(const Frame& F0, const bf16* URAW, int L, const float* cw, const float* cbias, const bf16* Wg, const float* ba, const float* bx, const float* spt,
;                                            bf16* LA, bf16* INP, float* HEND, float* PROD) {
;     ...
;                 for (int m = 0; m < 8; ++m) {
;                     float lr[4], xr[4], ea[4]; unsigned lwv[4], xwv[4];
;                     int gq = g; asm volatile("" : "+v"(gq));
;                     {
;                         f32x4 u4;
; #pragma unroll
;                         for (int e = 0; e < 4; ++e) u4[e] = bf2f(*(const LAS bf16*)(ut + (16 * m + 4 * gq + e) * RGF_PITCH + cl * 2));
;                         const f32x4 na = acc[m][np], nb2 = acc[m][2 + np]; f32x4 e1, e2;
; #pragma unroll
;                         for (int e = 0; e < 4; ++e) { e1[e] = fexp2_(fminf(na[e], 115.f)); e2[e] = fexp2_(fminf(nb2[e], 115.f)); }
;                         const f32x4 d1 = e1 + 1.0f, d2 = e2 + 1.0f, dp = d1 * d2; f32x4 rc;
; #pragma unroll
;                         for (int e = 0; e < 4; ++e) rc[e] = frcp_(dp[e]);
;                         const f32x4 l4 = (d2 * rc) * psp, ig = d1 * rc;
;                         const unsigned lw01 = pk2(l4[0], l4[1]), lw23 = pk2(l4[2], l4[3]);
;                         lr[0] = bflo(lw01); lr[1] = bfhi(lw01); lr[2] = bflo(lw23); lr[3] = bfhi(lw23);
;                         f32x4 ea4, sq;
; #pragma unroll
;                         for (int e = 0; e < 4; ++e) { ea4[e] = fexp2_(lr[e]); ea[e] = ea4[e]; }
; #pragma unroll
;                         for (int e = 0; e < 4; ++e) sq[e] = fsqrt_(__builtin_fabsf(__builtin_fmaf(-ea4[e], ea4[e], 1.0f)));
;                         const f32x4 x4 = sq * ig * u4;
;                         const unsigned xw01 = pk2(x4[0], x4[1]), xw23 = pk2(x4[2], x4[3]);
;                         xr[0] = bflo(xw01); xr[1] = bfhi(xw01); xr[2] = bflo(xw23); xr[3] = bfhi(xw23);
;                         lwv[0] = lw01 & 0xffffu; lwv[1] = lw01 >> 16; lwv[2] = lw23 & 0xffffu; lwv[3] = lw23 >> 16;
;                         xwv[0] = xw01 & 0xffffu; xwv[1] = xw01 >> 16; xwv[2] = xw23 & 0xffffu; xwv[3] = xw23 >> 16; }
; #pragma unroll
;                     for (int ep = 0; ep < 2; ++ep) { const bool odd = (Lq & 1) != 0; const int tok = 16 * m + 4 * gq + 2 * ep + (odd ? 1 : 0);
	v_exp_f32_e32 v243, v240
	v_fma_f32 v245, v241, v242, v170
	v_add_f32_e32 v153, v153, v240
	v_fma_f32 v244, v170, v243, v241
	v_cndmask_b32_e64 v170, v245, v244, s[38:39]
	ds_read_u16_d16_hi v144, v123 offset:33792
	ds_read_u16_d16_hi v145, v123 offset:34320
	ds_read_u16_d16_hi v146, v123 offset:34848
	ds_read_u16_d16_hi v147, v123 offset:35376
	v_min_f32_e32 v102, s20, v102
	v_min_f32_e32 v103, s20, v103
	v_min_f32_e32 v104, s20, v104
	v_min_f32_e32 v105, s20, v105
	v_min_f32_e32 v98, s20, v98
	v_min_f32_e32 v99, s20, v99
	v_min_f32_e32 v100, s20, v100
	v_min_f32_e32 v101, s20, v101
	v_exp_f32_e32 v102, v102
	v_exp_f32_e32 v103, v103
	v_exp_f32_e32 v104, v104
	v_exp_f32_e32 v105, v105
	v_exp_f32_e32 v98, v98
	v_exp_f32_e32 v99, v99
	v_exp_f32_e32 v100, v100
	v_exp_f32_e32 v101, v101
	v_pk_add_f32 v[102:103], v[102:103], 1.0 op_sel_hi:[1,0]
	v_pk_add_f32 v[104:105], v[104:105], 1.0 op_sel_hi:[1,0]
	v_pk_add_f32 v[98:99], v[98:99], 1.0 op_sel_hi:[1,0]
	v_pk_add_f32 v[100:101], v[100:101], 1.0 op_sel_hi:[1,0]
	v_pk_mul_f32 v[216:217], v[102:103], v[98:99]
	v_pk_mul_f32 v[218:219], v[104:105], v[100:101]
	v_rcp_f32_e32 v216, v216
	v_rcp_f32_e32 v217, v217
	v_rcp_f32_e32 v218, v218
	v_rcp_f32_e32 v219, v219
	v_pk_mul_f32 v[98:99], v[98:99], v[216:217]
	v_pk_mul_f32 v[100:101], v[100:101], v[218:219]
	v_pk_mul_f32 v[102:103], v[102:103], v[216:217]
	v_pk_mul_f32 v[104:105], v[104:105], v[218:219]
	v_pk_mul_f32 v[98:99], v[98:99], v[130:131] op_sel_hi:[1,0]
	v_pk_mul_f32 v[100:101], v[100:101], v[130:131] op_sel_hi:[1,0]
	v_cvt_pk_bf16_f32 v216, v98, v99
	v_cvt_pk_bf16_f32 v217, v100, v101
	v_lshlrev_b32_e32 v98, 16, v216
	v_lshlrev_b32_e32 v99, 16, v217
	v_and_b32_e32 v100, s21, v216
	v_and_b32_e32 v101, s21, v217
	v_exp_f32_e32 v222, v98
	v_exp_f32_e32 v223, v100
	v_exp_f32_e32 v224, v99
	v_exp_f32_e32 v225, v101
	s_waitcnt lgkmcnt(4)
	v_exp_f32_e32 v213, v210
	v_fma_f32 v215, v211, v212, v171
	v_add_f32_e32 v154, v154, v210
	v_fma_f32 v214, v171, v213, v211
	v_cndmask_b32_e64 v171, v215, v214, s[40:41]
	ds_bpermute_b32 v210, v177, v154
	v_exp_f32_e32 v212, v154
	ds_bpermute_b32 v211, v177, v171
	v_fma_f32 v218, -v222, v222, 1.0
	v_fma_f32 v219, -v223, v223, 1.0
	v_fma_f32 v220, -v224, v224, 1.0
	v_fma_f32 v221, -v225, v225, 1.0
	v_sqrt_f32_e64 v218, |v218|
	v_sqrt_f32_e64 v219, |v219|
	v_sqrt_f32_e64 v220, |v220|
	v_sqrt_f32_e64 v221, |v221|
	v_mov_b32_dpp v166, v216 quad_perm:[1,0,3,2] row_mask:0xf bank_mask:0xf bound_ctrl:1
	v_mov_b32_dpp v167, v217 quad_perm:[1,0,3,2] row_mask:0xf bank_mask:0xf bound_ctrl:1
	v_pk_mul_f32 v[218:219], v[218:219], v[102:103]
	v_pk_mul_f32 v[220:221], v[220:221], v[104:105]
	v_perm_b32 v236, v166, v216, v125
	v_perm_b32 v237, v167, v217, v125
	global_store_dword v126, v236, s[16:17] offset:0
	global_store_dword v127, v237, s[16:17] offset:0
	v_pk_mul_f32 v[218:219], v[218:219], v[148:149]
	v_pk_mul_f32 v[220:221], v[220:221], v[150:151]
	v_pk_add_f32 v[98:99], v[98:99], v[100:101]
	v_cvt_pk_bf16_f32 v102, v218, v219
	v_cvt_pk_bf16_f32 v103, v220, v221
	v_add_f32_e32 v155, v98, v99
	v_lshlrev_b32_e32 v218, 16, v102
	v_mov_b32_dpp v166, v102 quad_perm:[1,0,3,2] row_mask:0xf bank_mask:0xf bound_ctrl:1
	v_and_b32_e32 v219, s21, v102
	v_mov_b32_dpp v167, v103 quad_perm:[1,0,3,2] row_mask:0xf bank_mask:0xf bound_ctrl:1
	v_lshlrev_b32_e32 v220, 16, v103
	v_and_b32_e32 v221, s21, v103
	v_perm_b32 v238, v166, v102, v125
	v_perm_b32 v239, v167, v103, v125
	global_store_dword v126, v238, s[18:19] offset:0
	global_store_dword v127, v239, s[18:19] offset:0
	s_add_u32 s16, s16, 0x10000
	s_addc_u32 s17, s17, 0
	s_add_u32 s18, s18, 0x10000
	s_addc_u32 s19, s19, 0
	v_fma_f32 v244, v218, v223, v219
	v_fma_f32 v245, v221, v224, v220
	v_fma_f32 v244, v244, v224, v220
	v_fma_f32 v245, v245, v223, v219
	v_fma_f32 v244, v244, v225, v221
	v_fma_f32 v245, v245, v222, v218
	ds_bpermute_b32 v240, v129, v155
	v_cndmask_b32_e64 v172, v245, v244, s[30:31]
	v_exp_f32_e32 v242, v155
	ds_bpermute_b32 v241, v129, v172
	s_waitcnt lgkmcnt(2)
	v_exp_f32_e32 v213, v210
	v_fma_f32 v215, v211, v212, v171
	v_add_f32_e32 v154, v154, v210
	v_fma_f32 v214, v171, v213, v211
	v_cndmask_b32_e64 v171, v215, v214, s[38:39]
	ds_read_u16_d16_hi v148, v123 offset:42240
	ds_read_u16_d16_hi v149, v123 offset:42768
	ds_read_u16_d16_hi v150, v123 offset:43296
	ds_read_u16_d16_hi v151, v123 offset:43824
	v_min_f32_e32 v94, s20, v94
	v_min_f32_e32 v95, s20, v95
	v_min_f32_e32 v96, s20, v96
	v_min_f32_e32 v97, s20, v97
	v_min_f32_e32 v90, s20, v90
	v_min_f32_e32 v91, s20, v91
	v_min_f32_e32 v92, s20, v92
	v_min_f32_e32 v93, s20, v93
	v_exp_f32_e32 v94, v94
	v_exp_f32_e32 v95, v95
	v_exp_f32_e32 v96, v96
	v_exp_f32_e32 v97, v97
	v_exp_f32_e32 v90, v90
	v_exp_f32_e32 v91, v91
	v_exp_f32_e32 v92, v92
	v_exp_f32_e32 v93, v93
	v_pk_add_f32 v[94:95], v[94:95], 1.0 op_sel_hi:[1,0]
	v_pk_add_f32 v[96:97], v[96:97], 1.0 op_sel_hi:[1,0]
	v_pk_add_f32 v[90:91], v[90:91], 1.0 op_sel_hi:[1,0]
	v_pk_add_f32 v[92:93], v[92:93], 1.0 op_sel_hi:[1,0]
	v_pk_mul_f32 v[178:179], v[94:95], v[90:91]
	v_pk_mul_f32 v[180:181], v[96:97], v[92:93]
	v_rcp_f32_e32 v178, v178
	v_rcp_f32_e32 v179, v179
	v_rcp_f32_e32 v180, v180
	v_rcp_f32_e32 v181, v181
	v_pk_mul_f32 v[90:91], v[90:91], v[178:179]
	v_pk_mul_f32 v[92:93], v[92:93], v[180:181]
	v_pk_mul_f32 v[94:95], v[94:95], v[178:179]
	v_pk_mul_f32 v[96:97], v[96:97], v[180:181]
	v_pk_mul_f32 v[90:91], v[90:91], v[130:131] op_sel_hi:[1,0]
	v_pk_mul_f32 v[92:93], v[92:93], v[130:131] op_sel_hi:[1,0]
	v_cvt_pk_bf16_f32 v178, v90, v91
	v_cvt_pk_bf16_f32 v179, v92, v93
	v_lshlrev_b32_e32 v90, 16, v178
	v_lshlrev_b32_e32 v91, 16, v179
	v_and_b32_e32 v92, s21, v178
	v_and_b32_e32 v93, s21, v179
	v_exp_f32_e32 v184, v90
	v_exp_f32_e32 v185, v92
	v_exp_f32_e32 v186, v91
	v_exp_f32_e32 v187, v93
	s_waitcnt lgkmcnt(4)
; #define LAS __attribute__((address_space(3)))
; __device__ __forceinline__ void p_rg_fused(const Frame& F0, const bf16* URAW, int L, const float* cw, const float* cbias, const bf16* Wg, const float* ba, const float* bx, const float* spt,
;                                            bf16* LA, bf16* INP, float* HEND, float* PROD) {
;     ...
;                 for (int m = 0; m < 8; ++m) {
;                     float lr[4], xr[4], ea[4]; unsigned lwv[4], xwv[4];
;                     int gq = g; asm volatile("" : "+v"(gq));
;                     {
;                         f32x4 u4;
; #pragma unroll
;                         for (int e = 0; e < 4; ++e) u4[e] = bf2f(*(const LAS bf16*)(ut + (16 * m + 4 * gq + e) * RGF_PITCH + cl * 2));
;                         const f32x4 na = acc[m][np], nb2 = acc[m][2 + np]; f32x4 e1, e2;
; #pragma unroll
;                         for (int e = 0; e < 4; ++e) { e1[e] = fexp2_(fminf(na[e], 115.f)); e2[e] = fexp2_(fminf(nb2[e], 115.f)); }
;                         const f32x4 d1 = e1 + 1.0f, d2 = e2 + 1.0f, dp = d1 * d2; f32x4 rc;
; #pragma unroll
;                         for (int e = 0; e < 4; ++e) rc[e] = frcp_(dp[e]);
;                         const f32x4 l4 = (d2 * rc) * psp, ig = d1 * rc;
;                         const unsigned lw01 = pk2(l4[0], l4[1]), lw23 = pk2(l4[2], l4[3]);
;                         lr[0] = bflo(lw01); lr[1] = bfhi(lw01); lr[2] = bflo(lw23); lr[3] = bfhi(lw23);
;                         f32x4 ea4, sq;
; #pragma unroll
;                         for (int e = 0; e < 4; ++e) { ea4[e] = fexp2_(lr[e]); ea[e] = ea4[e]; }
; #pragma unroll
;                         for (int e = 0; e < 4; ++e) sq[e] = fsqrt_(__builtin_fabsf(__builtin_fmaf(-ea4[e], ea4[e], 1.0f)));
;                         const f32x4 x4 = sq * ig * u4;
;                         const unsigned xw01 = pk2(x4[0], x4[1]), xw23 = pk2(x4[2], x4[3]);
;                         xr[0] = bflo(xw01); xr[1] = bfhi(xw01); xr[2] = bflo(xw23); xr[3] = bfhi(xw23);
;                         lwv[0] = lw01 & 0xffffu; lwv[1] = lw01 >> 16; lwv[2] = lw23 & 0xffffu; lwv[3] = lw23 >> 16;
;                         xwv[0] = xw01 & 0xffffu; xwv[1] = xw01 >> 16; xwv[2] = xw23 & 0xffffu; xwv[3] = xw23 >> 16; }
; #pragma unroll
;                     for (int ep = 0; ep < 2; ++ep) { const bool odd = (Lq & 1) != 0; const int tok = 16 * m + 4 * gq + 2 * ep + (odd ? 1 : 0);
	v_exp_f32_e32 v243, v240
	v_fma_f32 v245, v241, v242, v172
	v_add_f32_e32 v155, v155, v240
	v_fma_f32 v244, v172, v243, v241
	v_cndmask_b32_e64 v172, v245, v244, s[40:41]
	ds_bpermute_b32 v240, v177, v155
	v_exp_f32_e32 v242, v155
	ds_bpermute_b32 v241, v177, v172
	v_fma_f32 v180, -v184, v184, 1.0
	v_fma_f32 v181, -v185, v185, 1.0
	v_fma_f32 v182, -v186, v186, 1.0
	v_fma_f32 v183, -v187, v187, 1.0
	v_sqrt_f32_e64 v180, |v180|
	v_sqrt_f32_e64 v181, |v181|
	v_sqrt_f32_e64 v182, |v182|
	v_sqrt_f32_e64 v183, |v183|
	v_mov_b32_dpp v188, v178 quad_perm:[1,0,3,2] row_mask:0xf bank_mask:0xf bound_ctrl:1
	v_mov_b32_dpp v165, v179 quad_perm:[1,0,3,2] row_mask:0xf bank_mask:0xf bound_ctrl:1
	v_pk_mul_f32 v[180:181], v[180:181], v[94:95]
	v_pk_mul_f32 v[182:183], v[182:183], v[96:97]
	v_perm_b32 v206, v188, v178, v125
	v_perm_b32 v207, v165, v179, v125
	global_store_dword v126, v206, s[16:17] offset:0
	global_store_dword v127, v207, s[16:17] offset:0
	v_pk_mul_f32 v[180:181], v[180:181], v[144:145]
	v_pk_mul_f32 v[182:183], v[182:183], v[146:147]
	v_pk_add_f32 v[90:91], v[90:91], v[92:93]
	v_cvt_pk_bf16_f32 v94, v180, v181
	v_cvt_pk_bf16_f32 v95, v182, v183
	v_add_f32_e32 v156, v90, v91
	v_lshlrev_b32_e32 v180, 16, v94
	v_mov_b32_dpp v188, v94 quad_perm:[1,0,3,2] row_mask:0xf bank_mask:0xf bound_ctrl:1
	v_and_b32_e32 v181, s21, v94
	v_mov_b32_dpp v165, v95 quad_perm:[1,0,3,2] row_mask:0xf bank_mask:0xf bound_ctrl:1
	v_lshlrev_b32_e32 v182, 16, v95
	v_and_b32_e32 v183, s21, v95
	v_perm_b32 v208, v188, v94, v125
	v_perm_b32 v209, v165, v95, v125
	global_store_dword v126, v208, s[18:19] offset:0
	global_store_dword v127, v209, s[18:19] offset:0
	s_add_u32 s16, s16, 0x10000
	s_addc_u32 s17, s17, 0
	s_add_u32 s18, s18, 0x10000
	s_addc_u32 s19, s19, 0
	v_fma_f32 v214, v180, v185, v181
	v_fma_f32 v215, v183, v186, v182
	v_fma_f32 v214, v214, v186, v182
	v_fma_f32 v215, v215, v185, v181
	v_fma_f32 v214, v214, v187, v183
	v_fma_f32 v215, v215, v184, v180
	ds_bpermute_b32 v210, v129, v156
	v_cndmask_b32_e64 v173, v215, v214, s[30:31]
	v_exp_f32_e32 v212, v156
	ds_bpermute_b32 v211, v129, v173
	s_waitcnt lgkmcnt(2)
	v_exp_f32_e32 v243, v240
	v_fma_f32 v245, v241, v242, v172
	v_add_f32_e32 v155, v155, v240
	v_fma_f32 v244, v172, v243, v241
	v_cndmask_b32_e64 v172, v245, v244, s[38:39]
	ds_read_u16_d16_hi v144, v123 offset:50688
	ds_read_u16_d16_hi v145, v123 offset:51216
	ds_read_u16_d16_hi v146, v123 offset:51744
	ds_read_u16_d16_hi v147, v123 offset:52272
	v_min_f32_e32 v86, s20, v86
	v_min_f32_e32 v87, s20, v87
	v_min_f32_e32 v88, s20, v88
	v_min_f32_e32 v89, s20, v89
	v_min_f32_e32 v82, s20, v82
	v_min_f32_e32 v83, s20, v83
	v_min_f32_e32 v84, s20, v84
	v_min_f32_e32 v85, s20, v85
	v_exp_f32_e32 v86, v86
	v_exp_f32_e32 v87, v87
	v_exp_f32_e32 v88, v88
	v_exp_f32_e32 v89, v89
	v_exp_f32_e32 v82, v82
	v_exp_f32_e32 v83, v83
	v_exp_f32_e32 v84, v84
	v_exp_f32_e32 v85, v85
	v_pk_add_f32 v[86:87], v[86:87], 1.0 op_sel_hi:[1,0]
	v_pk_add_f32 v[88:89], v[88:89], 1.0 op_sel_hi:[1,0]
	v_pk_add_f32 v[82:83], v[82:83], 1.0 op_sel_hi:[1,0]
	v_pk_add_f32 v[84:85], v[84:85], 1.0 op_sel_hi:[1,0]
	v_pk_mul_f32 v[216:217], v[86:87], v[82:83]
	v_pk_mul_f32 v[218:219], v[88:89], v[84:85]
	v_rcp_f32_e32 v216, v216
	v_rcp_f32_e32 v217, v217
	v_rcp_f32_e32 v218, v218
	v_rcp_f32_e32 v219, v219
	v_pk_mul_f32 v[82:83], v[82:83], v[216:217]
	v_pk_mul_f32 v[84:85], v[84:85], v[218:219]
	v_pk_mul_f32 v[86:87], v[86:87], v[216:217]
	v_pk_mul_f32 v[88:89], v[88:89], v[218:219]
	v_pk_mul_f32 v[82:83], v[82:83], v[130:131] op_sel_hi:[1,0]
	v_pk_mul_f32 v[84:85], v[84:85], v[130:131] op_sel_hi:[1,0]
	v_cvt_pk_bf16_f32 v216, v82, v83
	v_cvt_pk_bf16_f32 v217, v84, v85
	v_lshlrev_b32_e32 v82, 16, v216
	v_lshlrev_b32_e32 v83, 16, v217
	v_and_b32_e32 v84, s21, v216
	v_and_b32_e32 v85, s21, v217
	v_exp_f32_e32 v222, v82
	v_exp_f32_e32 v223, v84
	v_exp_f32_e32 v224, v83
	v_exp_f32_e32 v225, v85
	s_waitcnt lgkmcnt(4)
	v_exp_f32_e32 v213, v210
	v_fma_f32 v215, v211, v212, v173
	v_add_f32_e32 v156, v156, v210
	v_fma_f32 v214, v173, v213, v211
	v_cndmask_b32_e64 v173, v215, v214, s[40:41]
	ds_bpermute_b32 v210, v177, v156
	v_exp_f32_e32 v212, v156
	ds_bpermute_b32 v211, v177, v173
	v_fma_f32 v218, -v222, v222, 1.0
	v_fma_f32 v219, -v223, v223, 1.0
	v_fma_f32 v220, -v224, v224, 1.0
	v_fma_f32 v221, -v225, v225, 1.0
	v_sqrt_f32_e64 v218, |v218|
	v_sqrt_f32_e64 v219, |v219|
	v_sqrt_f32_e64 v220, |v220|
	v_sqrt_f32_e64 v221, |v221|
	v_mov_b32_dpp v166, v216 quad_perm:[1,0,3,2] row_mask:0xf bank_mask:0xf bound_ctrl:1
	v_mov_b32_dpp v167, v217 quad_perm:[1,0,3,2] row_mask:0xf bank_mask:0xf bound_ctrl:1
	v_pk_mul_f32 v[218:219], v[218:219], v[86:87]
	v_pk_mul_f32 v[220:221], v[220:221], v[88:89]
	v_perm_b32 v236, v166, v216, v125
	v_perm_b32 v237, v167, v217, v125
	global_store_dword v126, v236, s[16:17] offset:0
	global_store_dword v127, v237, s[16:17] offset:0
	v_pk_mul_f32 v[218:219], v[218:219], v[148:149]
	v_pk_mul_f32 v[220:221], v[220:221], v[150:151]
	v_pk_add_f32 v[82:83], v[82:83], v[84:85]
	v_cvt_pk_bf16_f32 v86, v218, v219
	v_cvt_pk_bf16_f32 v87, v220, v221
	v_add_f32_e32 v157, v82, v83
	v_lshlrev_b32_e32 v218, 16, v86
	v_mov_b32_dpp v166, v86 quad_perm:[1,0,3,2] row_mask:0xf bank_mask:0xf bound_ctrl:1
	v_and_b32_e32 v219, s21, v86
	v_mov_b32_dpp v167, v87 quad_perm:[1,0,3,2] row_mask:0xf bank_mask:0xf bound_ctrl:1
	v_lshlrev_b32_e32 v220, 16, v87
	v_and_b32_e32 v221, s21, v87
	v_perm_b32 v238, v166, v86, v125
	v_perm_b32 v239, v167, v87, v125
	global_store_dword v126, v238, s[18:19] offset:0
	global_store_dword v127, v239, s[18:19] offset:0
	s_add_u32 s16, s16, 0x10000
	s_addc_u32 s17, s17, 0
	s_add_u32 s18, s18, 0x10000
	s_addc_u32 s19, s19, 0
	v_fma_f32 v244, v218, v223, v219
	v_fma_f32 v245, v221, v224, v220
	v_fma_f32 v244, v244, v224, v220
	v_fma_f32 v245, v245, v223, v219
	v_fma_f32 v244, v244, v225, v221
	v_fma_f32 v245, v245, v222, v218
	ds_bpermute_b32 v240, v129, v157
	v_cndmask_b32_e64 v174, v245, v244, s[30:31]
	v_exp_f32_e32 v242, v157
	ds_bpermute_b32 v241, v129, v174
	s_waitcnt lgkmcnt(2)
; #define LAS __attribute__((address_space(3)))
; __device__ __forceinline__ void p_rg_fused(const Frame& F0, const bf16* URAW, int L, const float* cw, const float* cbias, const bf16* Wg, const float* ba, const float* bx, const float* spt,
;                                            bf16* LA, bf16* INP, float* HEND, float* PROD) {
;     ...
;                 for (int m = 0; m < 8; ++m) {
;                     float lr[4], xr[4], ea[4]; unsigned lwv[4], xwv[4];
;                     int gq = g; asm volatile("" : "+v"(gq));
;                     {
;                         f32x4 u4;
; #pragma unroll
;                         for (int e = 0; e < 4; ++e) u4[e] = bf2f(*(const LAS bf16*)(ut + (16 * m + 4 * gq + e) * RGF_PITCH + cl * 2));
;                         const f32x4 na = acc[m][np], nb2 = acc[m][2 + np]; f32x4 e1, e2;
; #pragma unroll
;                         for (int e = 0; e < 4; ++e) { e1[e] = fexp2_(fminf(na[e], 115.f)); e2[e] = fexp2_(fminf(nb2[e], 115.f)); }
;                         const f32x4 d1 = e1 + 1.0f, d2 = e2 + 1.0f, dp = d1 * d2; f32x4 rc;
; #pragma unroll
;                         for (int e = 0; e < 4; ++e) rc[e] = frcp_(dp[e]);
;                         const f32x4 l4 = (d2 * rc) * psp, ig = d1 * rc;
;                         const unsigned lw01 = pk2(l4[0], l4[1]), lw23 = pk2(l4[2], l4[3]);
;                         lr[0] = bflo(lw01); lr[1] = bfhi(lw01); lr[2] = bflo(lw23); lr[3] = bfhi(lw23);
;                         f32x4 ea4, sq;
; #pragma unroll
;                         for (int e = 0; e < 4; ++e) { ea4[e] = fexp2_(lr[e]); ea[e] = ea4[e]; }
; #pragma unroll
;                         for (int e = 0; e < 4; ++e) sq[e] = fsqrt_(__builtin_fabsf(__builtin_fmaf(-ea4[e], ea4[e], 1.0f)));
;                         const f32x4 x4 = sq * ig * u4;
;                         const unsigned xw01 = pk2(x4[0], x4[1]), xw23 = pk2(x4[2], x4[3]);
;                         xr[0] = bflo(xw01); xr[1] = bfhi(xw01); xr[2] = bflo(xw23); xr[3] = bfhi(xw23);
;                         lwv[0] = lw01 & 0xffffu; lwv[1] = lw01 >> 16; lwv[2] = lw23 & 0xffffu; lwv[3] = lw23 >> 16;
;                         xwv[0] = xw01 & 0xffffu; xwv[1] = xw01 >> 16; xwv[2] = xw23 & 0xffffu; xwv[3] = xw23 >> 16; }
; #pragma unroll
;                     for (int ep = 0; ep < 2; ++ep) { const bool odd = (Lq & 1) != 0; const int tok = 16 * m + 4 * gq + 2 * ep + (odd ? 1 : 0);
	v_exp_f32_e32 v213, v210
	v_fma_f32 v215, v211, v212, v173
	v_add_f32_e32 v156, v156, v210
	v_fma_f32 v214, v173, v213, v211
	v_cndmask_b32_e64 v173, v215, v214, s[38:39]
	ds_read_u16_d16_hi v148, v123 offset:59136
	ds_read_u16_d16_hi v149, v123 offset:59664
	ds_read_u16_d16_hi v150, v123 offset:60192
	ds_read_u16_d16_hi v151, v123 offset:60720
	v_min_f32_e32 v78, s20, v78
	v_min_f32_e32 v79, s20, v79
	v_min_f32_e32 v80, s20, v80
	v_min_f32_e32 v81, s20, v81
	v_min_f32_e32 v74, s20, v74
	v_min_f32_e32 v75, s20, v75
	v_min_f32_e32 v76, s20, v76
	v_min_f32_e32 v77, s20, v77
	v_exp_f32_e32 v78, v78
	v_exp_f32_e32 v79, v79
	v_exp_f32_e32 v80, v80
	v_exp_f32_e32 v81, v81
	v_exp_f32_e32 v74, v74
	v_exp_f32_e32 v75, v75
	v_exp_f32_e32 v76, v76
	v_exp_f32_e32 v77, v77
	v_pk_add_f32 v[78:79], v[78:79], 1.0 op_sel_hi:[1,0]
	v_pk_add_f32 v[80:81], v[80:81], 1.0 op_sel_hi:[1,0]
	v_pk_add_f32 v[74:75], v[74:75], 1.0 op_sel_hi:[1,0]
	v_pk_add_f32 v[76:77], v[76:77], 1.0 op_sel_hi:[1,0]
	v_pk_mul_f32 v[178:179], v[78:79], v[74:75]
	v_pk_mul_f32 v[180:181], v[80:81], v[76:77]
	v_rcp_f32_e32 v178, v178
	v_rcp_f32_e32 v179, v179
	v_rcp_f32_e32 v180, v180
	v_rcp_f32_e32 v181, v181
	v_pk_mul_f32 v[74:75], v[74:75], v[178:179]
	v_pk_mul_f32 v[76:77], v[76:77], v[180:181]
	v_pk_mul_f32 v[78:79], v[78:79], v[178:179]
	v_pk_mul_f32 v[80:81], v[80:81], v[180:181]
	v_pk_mul_f32 v[74:75], v[74:75], v[130:131] op_sel_hi:[1,0]
	v_pk_mul_f32 v[76:77], v[76:77], v[130:131] op_sel_hi:[1,0]
	v_cvt_pk_bf16_f32 v178, v74, v75
	v_cvt_pk_bf16_f32 v179, v76, v77
	v_lshlrev_b32_e32 v74, 16, v178
	v_lshlrev_b32_e32 v75, 16, v179
	v_and_b32_e32 v76, s21, v178
	v_and_b32_e32 v77, s21, v179
	v_exp_f32_e32 v184, v74
	v_exp_f32_e32 v185, v76
	v_exp_f32_e32 v186, v75
	v_exp_f32_e32 v187, v77
	s_waitcnt lgkmcnt(4)
	v_exp_f32_e32 v243, v240
	v_fma_f32 v245, v241, v242, v174
	v_add_f32_e32 v157, v157, v240
	v_fma_f32 v244, v174, v243, v241
	v_cndmask_b32_e64 v174, v245, v244, s[40:41]
	ds_bpermute_b32 v240, v177, v157
	v_exp_f32_e32 v242, v157
	ds_bpermute_b32 v241, v177, v174
	v_fma_f32 v180, -v184, v184, 1.0
	v_fma_f32 v181, -v185, v185, 1.0
	v_fma_f32 v182, -v186, v186, 1.0
	v_fma_f32 v183, -v187, v187, 1.0
	v_sqrt_f32_e64 v180, |v180|
	v_sqrt_f32_e64 v181, |v181|
	v_sqrt_f32_e64 v182, |v182|
	v_sqrt_f32_e64 v183, |v183|
	v_mov_b32_dpp v188, v178 quad_perm:[1,0,3,2] row_mask:0xf bank_mask:0xf bound_ctrl:1
	v_mov_b32_dpp v165, v179 quad_perm:[1,0,3,2] row_mask:0xf bank_mask:0xf bound_ctrl:1
	v_pk_mul_f32 v[180:181], v[180:181], v[78:79]
	v_pk_mul_f32 v[182:183], v[182:183], v[80:81]
	v_perm_b32 v206, v188, v178, v125
	v_perm_b32 v207, v165, v179, v125
	global_store_dword v126, v206, s[16:17] offset:0
	global_store_dword v127, v207, s[16:17] offset:0
	v_pk_mul_f32 v[180:181], v[180:181], v[144:145]
	v_pk_mul_f32 v[182:183], v[182:183], v[146:147]
	v_pk_add_f32 v[74:75], v[74:75], v[76:77]
	v_cvt_pk_bf16_f32 v78, v180, v181
	v_cvt_pk_bf16_f32 v79, v182, v183
	v_add_f32_e32 v246, v74, v75
	v_lshlrev_b32_e32 v180, 16, v78
	v_mov_b32_dpp v188, v78 quad_perm:[1,0,3,2] row_mask:0xf bank_mask:0xf bound_ctrl:1
	v_and_b32_e32 v181, s21, v78
	v_mov_b32_dpp v165, v79 quad_perm:[1,0,3,2] row_mask:0xf bank_mask:0xf bound_ctrl:1
	v_lshlrev_b32_e32 v182, 16, v79
	v_and_b32_e32 v183, s21, v79
	v_perm_b32 v208, v188, v78, v125
	v_perm_b32 v209, v165, v79, v125
	global_store_dword v126, v208, s[18:19] offset:0
	global_store_dword v127, v209, s[18:19] offset:0
	s_add_u32 s16, s16, 0x10000
	s_addc_u32 s17, s17, 0
	s_add_u32 s18, s18, 0x10000
	s_addc_u32 s19, s19, 0
	v_fma_f32 v214, v180, v185, v181
	v_fma_f32 v215, v183, v186, v182
	v_fma_f32 v214, v214, v186, v182
	v_fma_f32 v215, v215, v185, v181
	v_fma_f32 v214, v214, v187, v183
	v_fma_f32 v215, v215, v184, v180
	ds_bpermute_b32 v210, v129, v246
	v_cndmask_b32_e64 v175, v215, v214, s[30:31]
	v_exp_f32_e32 v212, v246
	ds_bpermute_b32 v211, v129, v175
	s_waitcnt lgkmcnt(2)
	v_exp_f32_e32 v243, v240
	v_fma_f32 v245, v241, v242, v174
	v_add_f32_e32 v157, v157, v240
	v_fma_f32 v244, v174, v243, v241
	v_cndmask_b32_e64 v174, v245, v244, s[38:39]
	v_min_f32_e32 v70, s20, v70
	v_min_f32_e32 v71, s20, v71
	v_min_f32_e32 v72, s20, v72
	v_min_f32_e32 v73, s20, v73
	v_min_f32_e32 v66, s20, v66
	v_min_f32_e32 v67, s20, v67
	v_min_f32_e32 v68, s20, v68
	v_min_f32_e32 v69, s20, v69
	v_exp_f32_e32 v70, v70
	v_exp_f32_e32 v71, v71
	v_exp_f32_e32 v72, v72
	v_exp_f32_e32 v73, v73
	v_exp_f32_e32 v66, v66
	v_exp_f32_e32 v67, v67
	v_exp_f32_e32 v68, v68
	v_exp_f32_e32 v69, v69
	v_pk_add_f32 v[70:71], v[70:71], 1.0 op_sel_hi:[1,0]
	v_pk_add_f32 v[72:73], v[72:73], 1.0 op_sel_hi:[1,0]
	v_pk_add_f32 v[66:67], v[66:67], 1.0 op_sel_hi:[1,0]
	v_pk_add_f32 v[68:69], v[68:69], 1.0 op_sel_hi:[1,0]
	v_pk_mul_f32 v[216:217], v[70:71], v[66:67]
	v_pk_mul_f32 v[218:219], v[72:73], v[68:69]
	v_rcp_f32_e32 v216, v216
	v_rcp_f32_e32 v217, v217
	v_rcp_f32_e32 v218, v218
	v_rcp_f32_e32 v219, v219
	v_pk_mul_f32 v[66:67], v[66:67], v[216:217]
	v_pk_mul_f32 v[68:69], v[68:69], v[218:219]
	v_pk_mul_f32 v[70:71], v[70:71], v[216:217]
	v_pk_mul_f32 v[72:73], v[72:73], v[218:219]
	v_pk_mul_f32 v[66:67], v[66:67], v[130:131] op_sel_hi:[1,0]
	v_pk_mul_f32 v[68:69], v[68:69], v[130:131] op_sel_hi:[1,0]
	v_cvt_pk_bf16_f32 v216, v66, v67
	v_cvt_pk_bf16_f32 v217, v68, v69
	v_lshlrev_b32_e32 v66, 16, v216
	v_lshlrev_b32_e32 v67, 16, v217
	v_and_b32_e32 v68, s21, v216
	v_and_b32_e32 v69, s21, v217
	v_exp_f32_e32 v222, v66
	v_exp_f32_e32 v223, v68
	v_exp_f32_e32 v224, v67
	v_exp_f32_e32 v225, v69
	s_waitcnt lgkmcnt(0)
; #define LAS __attribute__((address_space(3)))
; __device__ __forceinline__ void p_rg_fused(const Frame& F0, const bf16* URAW, int L, const float* cw, const float* cbias, const bf16* Wg, const float* ba, const float* bx, const float* spt,
;                                            bf16* LA, bf16* INP, float* HEND, float* PROD) {
;     ...
;                 for (int m = 0; m < 8; ++m) {
;                     float lr[4], xr[4], ea[4]; unsigned lwv[4], xwv[4];
;                     int gq = g; asm volatile("" : "+v"(gq));
;                     {
;                         f32x4 u4;
; #pragma unroll
;                         for (int e = 0; e < 4; ++e) u4[e] = bf2f(*(const LAS bf16*)(ut + (16 * m + 4 * gq + e) * RGF_PITCH + cl * 2));
;                         const f32x4 na = acc[m][np], nb2 = acc[m][2 + np]; f32x4 e1, e2;
; #pragma unroll
;                         for (int e = 0; e < 4; ++e) { e1[e] = fexp2_(fminf(na[e], 115.f)); e2[e] = fexp2_(fminf(nb2[e], 115.f)); }
;                         const f32x4 d1 = e1 + 1.0f, d2 = e2 + 1.0f, dp = d1 * d2; f32x4 rc;
; #pragma unroll
;                         for (int e = 0; e < 4; ++e) rc[e] = frcp_(dp[e]);
;                         const f32x4 l4 = (d2 * rc) * psp, ig = d1 * rc;
;                         const unsigned lw01 = pk2(l4[0], l4[1]), lw23 = pk2(l4[2], l4[3]);
;                         lr[0] = bflo(lw01); lr[1] = bfhi(lw01); lr[2] = bflo(lw23); lr[3] = bfhi(lw23);
;                         f32x4 ea4, sq;
; #pragma unroll
;                         for (int e = 0; e < 4; ++e) { ea4[e] = fexp2_(lr[e]); ea[e] = ea4[e]; }
; #pragma unroll
;                         for (int e = 0; e < 4; ++e) sq[e] = fsqrt_(__builtin_fabsf(__builtin_fmaf(-ea4[e], ea4[e], 1.0f)));
;                         const f32x4 x4 = sq * ig * u4;
;                         const unsigned xw01 = pk2(x4[0], x4[1]), xw23 = pk2(x4[2], x4[3]);
;                         xr[0] = bflo(xw01); xr[1] = bfhi(xw01); xr[2] = bflo(xw23); xr[3] = bfhi(xw23);
;                         lwv[0] = lw01 & 0xffffu; lwv[1] = lw01 >> 16; lwv[2] = lw23 & 0xffffu; lwv[3] = lw23 >> 16;
;                         xwv[0] = xw01 & 0xffffu; xwv[1] = xw01 >> 16; xwv[2] = xw23 & 0xffffu; xwv[3] = xw23 >> 16; }
; #pragma unroll
;                     for (int ep = 0; ep < 2; ++ep) { const bool odd = (Lq & 1) != 0; const int tok = 16 * m + 4 * gq + 2 * ep + (odd ? 1 : 0);
	v_exp_f32_e32 v213, v210
	v_fma_f32 v215, v211, v212, v175
	v_add_f32_e32 v246, v246, v210
	v_fma_f32 v214, v175, v213, v211
	v_cndmask_b32_e64 v175, v215, v214, s[40:41]
	ds_bpermute_b32 v210, v177, v246
	v_exp_f32_e32 v212, v246
	ds_bpermute_b32 v211, v177, v175
	v_fma_f32 v218, -v222, v222, 1.0
	v_fma_f32 v219, -v223, v223, 1.0
	v_fma_f32 v220, -v224, v224, 1.0
	v_fma_f32 v221, -v225, v225, 1.0
	v_sqrt_f32_e64 v218, |v218|
	v_sqrt_f32_e64 v219, |v219|
	v_sqrt_f32_e64 v220, |v220|
	v_sqrt_f32_e64 v221, |v221|
	v_mov_b32_dpp v166, v216 quad_perm:[1,0,3,2] row_mask:0xf bank_mask:0xf bound_ctrl:1
	v_mov_b32_dpp v167, v217 quad_perm:[1,0,3,2] row_mask:0xf bank_mask:0xf bound_ctrl:1
	v_pk_mul_f32 v[218:219], v[218:219], v[70:71]
	v_pk_mul_f32 v[220:221], v[220:221], v[72:73]
	v_perm_b32 v236, v166, v216, v125
	v_perm_b32 v237, v167, v217, v125
	global_store_dword v126, v236, s[16:17] offset:0
	global_store_dword v127, v237, s[16:17] offset:0
	v_pk_mul_f32 v[218:219], v[218:219], v[148:149]
	v_pk_mul_f32 v[220:221], v[220:221], v[150:151]
	v_pk_add_f32 v[66:67], v[66:67], v[68:69]
	v_cvt_pk_bf16_f32 v70, v218, v219
	v_cvt_pk_bf16_f32 v71, v220, v221
	v_add_f32_e32 v247, v66, v67
	v_lshlrev_b32_e32 v218, 16, v70
	v_mov_b32_dpp v166, v70 quad_perm:[1,0,3,2] row_mask:0xf bank_mask:0xf bound_ctrl:1
	v_and_b32_e32 v219, s21, v70
	v_mov_b32_dpp v167, v71 quad_perm:[1,0,3,2] row_mask:0xf bank_mask:0xf bound_ctrl:1
	v_lshlrev_b32_e32 v220, 16, v71
	v_and_b32_e32 v221, s21, v71
	v_perm_b32 v238, v166, v70, v125
	v_perm_b32 v239, v167, v71, v125
	global_store_dword v126, v238, s[18:19] offset:0
	global_store_dword v127, v239, s[18:19] offset:0
	v_fma_f32 v244, v218, v223, v219
	v_fma_f32 v245, v221, v224, v220
	v_fma_f32 v244, v244, v224, v220
	v_fma_f32 v245, v245, v223, v219
	v_fma_f32 v244, v244, v225, v221
	v_fma_f32 v245, v245, v222, v218
	ds_bpermute_b32 v240, v129, v247
	v_cndmask_b32_e64 v176, v245, v244, s[30:31]
	v_exp_f32_e32 v242, v247
	ds_bpermute_b32 v241, v129, v176
	s_waitcnt lgkmcnt(2)
	v_exp_f32_e32 v213, v210
	v_fma_f32 v215, v211, v212, v175
	v_add_f32_e32 v246, v246, v210
	v_fma_f32 v214, v175, v213, v211
	v_cndmask_b32_e64 v175, v215, v214, s[38:39]
	s_waitcnt lgkmcnt(0)
	v_exp_f32_e32 v243, v240
	v_fma_f32 v245, v241, v242, v176
	v_add_f32_e32 v247, v247, v240
	v_fma_f32 v244, v176, v243, v241
	v_cndmask_b32_e64 v176, v245, v244, s[40:41]
	ds_bpermute_b32 v240, v177, v247
	v_exp_f32_e32 v242, v247
	ds_bpermute_b32 v241, v177, v176
	s_waitcnt lgkmcnt(0)
	v_exp_f32_e32 v243, v240
	v_fma_f32 v245, v241, v242, v176
	v_add_f32_e32 v247, v247, v240
	v_fma_f32 v244, v176, v243, v241
	v_cndmask_b32_e64 v176, v245, v244, s[38:39]
	v_add_f32_e32 v178, v152, v153
	v_add_f32_e32 v179, v154, v155
	v_add_f32_e32 v180, v156, v157
	v_add_f32_e32 v181, v246, v247
	v_add_f32_e32 v178, v178, v179
	v_add_f32_e32 v180, v180, v181
	v_exp_f32_e32 v178, v178
	v_exp_f32_e32 v180, v180
	s_cmp_lg_u32 s10, 0
	s_cbranch_scc1 .Lrgx_bwd_np0
	v_exp_f32_e32 v184, v153
	v_exp_f32_e32 v185, v154
	v_exp_f32_e32 v186, v155
	v_exp_f32_e32 v222, v157
	v_exp_f32_e32 v223, v246
	v_exp_f32_e32 v224, v247
	v_fma_f32 v214, v169, v184, v170
	v_fma_f32 v215, v173, v222, v174
	v_fma_f32 v214, v214, v185, v171
	v_fma_f32 v215, v215, v223, v175
	v_fma_f32 v214, v214, v186, v172
	v_fma_f32 v215, v215, v224, v176
	s_branch .Lrgx_st_np0
.Lrgx_bwd_np0:
	v_exp_f32_e32 v186, v154
	v_exp_f32_e32 v185, v153
	v_exp_f32_e32 v184, v152
	v_exp_f32_e32 v224, v246
	v_exp_f32_e32 v223, v157
	v_exp_f32_e32 v222, v156
	v_fma_f32 v214, v172, v186, v171
	v_fma_f32 v215, v176, v224, v175
	v_fma_f32 v214, v214, v185, v170
	v_fma_f32 v215, v215, v223, v174
	v_fma_f32 v214, v214, v184, v169
	v_fma_f32 v215, v215, v222, v173
.Lrgx_st_np0:
	s_lshl_b32 s22, s10, 13
	s_lshl_b64 s[0:1], s[24:25], 2
	s_add_u32 s0, s0, s22
	s_addc_u32 s1, s1, 0
	s_lshl_b64 s[16:17], s[26:27], 2
	s_add_u32 s16, s16, s22
	s_addc_u32 s17, s17, 0
	s_add_u32 s18, s8, s0
	s_addc_u32 s19, s9, s1
	s_add_u32 s0, s6, s0
	s_addc_u32 s1, s7, s1
	s_add_u32 s22, s8, s16
	s_addc_u32 s23, s9, s17
	s_add_u32 s16, s6, s16
	s_addc_u32 s17, s7, s17
	s_mov_b64 vcc, exec
	s_and_b64 exec, exec, s[42:43]
	global_store_dword v128, v214, s[18:19] offset:0
	global_store_dword v128, v178, s[0:1] offset:0
	global_store_dword v128, v215, s[22:23] offset:0
	global_store_dword v128, v180, s[16:17] offset:0
	s_mov_b64 exec, vcc
	s_lshl_b32 s0, s10, 25
	s_add_u32 s16, s61, s0
	s_addc_u32 s17, s71, 0
	s_add_u32 s18, s65, s0
	s_addc_u32 s19, s72, 0
	ds_read_u16_d16_hi v144, v123 offset:32
	ds_read_u16_d16_hi v145, v123 offset:560
	ds_read_u16_d16_hi v146, v123 offset:1088
	ds_read_u16_d16_hi v147, v123 offset:1616
	ds_read_u16_d16_hi v148, v123 offset:8480
	ds_read_u16_d16_hi v149, v123 offset:9008
	ds_read_u16_d16_hi v150, v123 offset:9536
	ds_read_u16_d16_hi v151, v123 offset:10064
	v_min_f32_e32 v62, s20, v62
	v_min_f32_e32 v63, s20, v63
	v_min_f32_e32 v64, s20, v64
	v_min_f32_e32 v65, s20, v65
	v_min_f32_e32 v58, s20, v58
	v_min_f32_e32 v59, s20, v59
	v_min_f32_e32 v60, s20, v60
	v_min_f32_e32 v61, s20, v61
	v_exp_f32_e32 v62, v62
	v_exp_f32_e32 v63, v63
	v_exp_f32_e32 v64, v64
	v_exp_f32_e32 v65, v65
	v_exp_f32_e32 v58, v58
	v_exp_f32_e32 v59, v59
	v_exp_f32_e32 v60, v60
	v_exp_f32_e32 v61, v61
	v_pk_add_f32 v[62:63], v[62:63], 1.0 op_sel_hi:[1,0]
	v_pk_add_f32 v[64:65], v[64:65], 1.0 op_sel_hi:[1,0]
	v_pk_add_f32 v[58:59], v[58:59], 1.0 op_sel_hi:[1,0]
	v_pk_add_f32 v[60:61], v[60:61], 1.0 op_sel_hi:[1,0]
	v_pk_mul_f32 v[178:179], v[62:63], v[58:59]
	v_pk_mul_f32 v[180:181], v[64:65], v[60:61]
	v_rcp_f32_e32 v178, v178
	v_rcp_f32_e32 v179, v179
	v_rcp_f32_e32 v180, v180
	v_rcp_f32_e32 v181, v181
	v_pk_mul_f32 v[58:59], v[58:59], v[178:179]
	v_pk_mul_f32 v[60:61], v[60:61], v[180:181]
	v_pk_mul_f32 v[62:63], v[62:63], v[178:179]
	v_pk_mul_f32 v[64:65], v[64:65], v[180:181]
	v_pk_mul_f32 v[58:59], v[58:59], v[158:159] op_sel_hi:[1,0]
	v_pk_mul_f32 v[60:61], v[60:61], v[158:159] op_sel_hi:[1,0]
	v_cvt_pk_bf16_f32 v178, v58, v59
	v_cvt_pk_bf16_f32 v179, v60, v61
	v_lshlrev_b32_e32 v58, 16, v178
	v_lshlrev_b32_e32 v59, 16, v179
	v_and_b32_e32 v60, s21, v178
	v_and_b32_e32 v61, s21, v179
	v_exp_f32_e32 v184, v58
	v_exp_f32_e32 v185, v60
	v_exp_f32_e32 v186, v59
	v_exp_f32_e32 v187, v61
	v_fma_f32 v180, -v184, v184, 1.0
	v_fma_f32 v181, -v185, v185, 1.0
	v_fma_f32 v182, -v186, v186, 1.0
	v_fma_f32 v183, -v187, v187, 1.0
	v_sqrt_f32_e64 v180, |v180|
	v_sqrt_f32_e64 v181, |v181|
	v_sqrt_f32_e64 v182, |v182|
	v_sqrt_f32_e64 v183, |v183|
	v_mov_b32_dpp v188, v178 quad_perm:[1,0,3,2] row_mask:0xf bank_mask:0xf bound_ctrl:1
	v_mov_b32_dpp v165, v179 quad_perm:[1,0,3,2] row_mask:0xf bank_mask:0xf bound_ctrl:1
	v_pk_mul_f32 v[180:181], v[180:181], v[62:63]
	v_pk_mul_f32 v[182:183], v[182:183], v[64:65]
	v_perm_b32 v206, v188, v178, v125
	v_perm_b32 v207, v165, v179, v125
	global_store_dword v126, v206, s[16:17] offset:32
	global_store_dword v127, v207, s[16:17] offset:32
	s_waitcnt lgkmcnt(4)
; #define LAS __attribute__((address_space(3)))
; __device__ __forceinline__ void p_rg_fused(const Frame& F0, const bf16* URAW, int L, const float* cw, const float* cbias, const bf16* Wg, const float* ba, const float* bx, const float* spt,
;                                            bf16* LA, bf16* INP, float* HEND, float* PROD) {
;     ...
;                 for (int m = 0; m < 8; ++m) {
;                     float lr[4], xr[4], ea[4]; unsigned lwv[4], xwv[4];
;                     int gq = g; asm volatile("" : "+v"(gq));
;                     {
;                         f32x4 u4;
; #pragma unroll
;                         for (int e = 0; e < 4; ++e) u4[e] = bf2f(*(const LAS bf16*)(ut + (16 * m + 4 * gq + e) * RGF_PITCH + cl * 2));
;                         const f32x4 na = acc[m][np], nb2 = acc[m][2 + np]; f32x4 e1, e2;
; #pragma unroll
;                         for (int e = 0; e < 4; ++e) { e1[e] = fexp2_(fminf(na[e], 115.f)); e2[e] = fexp2_(fminf(nb2[e], 115.f)); }
;                         const f32x4 d1 = e1 + 1.0f, d2 = e2 + 1.0f, dp = d1 * d2; f32x4 rc;
; #pragma unroll
;                         for (int e = 0; e < 4; ++e) rc[e] = frcp_(dp[e]);
;                         const f32x4 l4 = (d2 * rc) * psp, ig = d1 * rc;
;                         const unsigned lw01 = pk2(l4[0], l4[1]), lw23 = pk2(l4[2], l4[3]);
;                         lr[0] = bflo(lw01); lr[1] = bfhi(lw01); lr[2] = bflo(lw23); lr[3] = bfhi(lw23);
;                         f32x4 ea4, sq;
; #pragma unroll
;                         for (int e = 0; e < 4; ++e) { ea4[e] = fexp2_(lr[e]); ea[e] = ea4[e]; }
; #pragma unroll
;                         for (int e = 0; e < 4; ++e) sq[e] = fsqrt_(__builtin_fabsf(__builtin_fmaf(-ea4[e], ea4[e], 1.0f)));
;                         const f32x4 x4 = sq * ig * u4;
;                         const unsigned xw01 = pk2(x4[0], x4[1]), xw23 = pk2(x4[2], x4[3]);
;                         xr[0] = bflo(xw01); xr[1] = bfhi(xw01); xr[2] = bflo(xw23); xr[3] = bfhi(xw23);
;                         lwv[0] = lw01 & 0xffffu; lwv[1] = lw01 >> 16; lwv[2] = lw23 & 0xffffu; lwv[3] = lw23 >> 16;
;                         xwv[0] = xw01 & 0xffffu; xwv[1] = xw01 >> 16; xwv[2] = xw23 & 0xffffu; xwv[3] = xw23 >> 16; }
; #pragma unroll
;                     for (int ep = 0; ep < 2; ++ep) { const bool odd = (Lq & 1) != 0; const int tok = 16 * m + 4 * gq + 2 * ep + (odd ? 1 : 0);
	v_pk_mul_f32 v[180:181], v[180:181], v[144:145]
	v_pk_mul_f32 v[182:183], v[182:183], v[146:147]
	v_pk_add_f32 v[58:59], v[58:59], v[60:61]
	v_cvt_pk_bf16_f32 v62, v180, v181
	v_cvt_pk_bf16_f32 v63, v182, v183
	v_add_f32_e32 v152, v58, v59
	v_lshlrev_b32_e32 v180, 16, v62
	v_mov_b32_dpp v188, v62 quad_perm:[1,0,3,2] row_mask:0xf bank_mask:0xf bound_ctrl:1
	v_and_b32_e32 v181, s21, v62
	v_mov_b32_dpp v165, v63 quad_perm:[1,0,3,2] row_mask:0xf bank_mask:0xf bound_ctrl:1
	v_lshlrev_b32_e32 v182, 16, v63
	v_and_b32_e32 v183, s21, v63
	v_perm_b32 v208, v188, v62, v125
	v_perm_b32 v209, v165, v63, v125
	global_store_dword v126, v208, s[18:19] offset:32
	global_store_dword v127, v209, s[18:19] offset:32
	s_add_u32 s16, s16, 0x10000
	s_addc_u32 s17, s17, 0
	s_add_u32 s18, s18, 0x10000
	s_addc_u32 s19, s19, 0
	v_fma_f32 v214, v180, v185, v181
	v_fma_f32 v215, v183, v186, v182
	v_fma_f32 v214, v214, v186, v182
	v_fma_f32 v215, v215, v185, v181
	v_fma_f32 v214, v214, v187, v183
	v_fma_f32 v215, v215, v184, v180
	ds_bpermute_b32 v210, v129, v152
	v_cndmask_b32_e64 v169, v215, v214, s[30:31]
	v_exp_f32_e32 v212, v152
	ds_bpermute_b32 v211, v129, v169
	ds_read_u16_d16_hi v144, v123 offset:16928
	ds_read_u16_d16_hi v145, v123 offset:17456
	ds_read_u16_d16_hi v146, v123 offset:17984
	ds_read_u16_d16_hi v147, v123 offset:18512
	v_min_f32_e32 v54, s20, v54
	v_min_f32_e32 v55, s20, v55
	v_min_f32_e32 v56, s20, v56
	v_min_f32_e32 v57, s20, v57
	v_min_f32_e32 v50, s20, v50
	v_min_f32_e32 v51, s20, v51
	v_min_f32_e32 v52, s20, v52
	v_min_f32_e32 v53, s20, v53
	v_exp_f32_e32 v54, v54
	v_exp_f32_e32 v55, v55
	v_exp_f32_e32 v56, v56
	v_exp_f32_e32 v57, v57
	v_exp_f32_e32 v50, v50
	v_exp_f32_e32 v51, v51
	v_exp_f32_e32 v52, v52
	v_exp_f32_e32 v53, v53
	v_pk_add_f32 v[54:55], v[54:55], 1.0 op_sel_hi:[1,0]
	v_pk_add_f32 v[56:57], v[56:57], 1.0 op_sel_hi:[1,0]
	v_pk_add_f32 v[50:51], v[50:51], 1.0 op_sel_hi:[1,0]
	v_pk_add_f32 v[52:53], v[52:53], 1.0 op_sel_hi:[1,0]
	v_pk_mul_f32 v[216:217], v[54:55], v[50:51]
	v_pk_mul_f32 v[218:219], v[56:57], v[52:53]
	v_rcp_f32_e32 v216, v216
	v_rcp_f32_e32 v217, v217
	v_rcp_f32_e32 v218, v218
	v_rcp_f32_e32 v219, v219
	v_pk_mul_f32 v[50:51], v[50:51], v[216:217]
	v_pk_mul_f32 v[52:53], v[52:53], v[218:219]
	v_pk_mul_f32 v[54:55], v[54:55], v[216:217]
	v_pk_mul_f32 v[56:57], v[56:57], v[218:219]
	v_pk_mul_f32 v[50:51], v[50:51], v[158:159] op_sel_hi:[1,0]
	v_pk_mul_f32 v[52:53], v[52:53], v[158:159] op_sel_hi:[1,0]
	v_cvt_pk_bf16_f32 v216, v50, v51
	v_cvt_pk_bf16_f32 v217, v52, v53
	v_lshlrev_b32_e32 v50, 16, v216
	v_lshlrev_b32_e32 v51, 16, v217
	v_and_b32_e32 v52, s21, v216
	v_and_b32_e32 v53, s21, v217
	v_exp_f32_e32 v222, v50
	v_exp_f32_e32 v223, v52
	v_exp_f32_e32 v224, v51
	v_exp_f32_e32 v225, v53
	s_waitcnt lgkmcnt(4)
	v_exp_f32_e32 v213, v210
	v_fma_f32 v215, v211, v212, v169
	v_add_f32_e32 v152, v152, v210
	v_fma_f32 v214, v169, v213, v211
	v_cndmask_b32_e64 v169, v215, v214, s[40:41]
	ds_bpermute_b32 v210, v177, v152
	v_exp_f32_e32 v212, v152
	ds_bpermute_b32 v211, v177, v169
	v_fma_f32 v218, -v222, v222, 1.0
	v_fma_f32 v219, -v223, v223, 1.0
	v_fma_f32 v220, -v224, v224, 1.0
	v_fma_f32 v221, -v225, v225, 1.0
	v_sqrt_f32_e64 v218, |v218|
	v_sqrt_f32_e64 v219, |v219|
	v_sqrt_f32_e64 v220, |v220|
	v_sqrt_f32_e64 v221, |v221|
	v_mov_b32_dpp v166, v216 quad_perm:[1,0,3,2] row_mask:0xf bank_mask:0xf bound_ctrl:1
	v_mov_b32_dpp v167, v217 quad_perm:[1,0,3,2] row_mask:0xf bank_mask:0xf bound_ctrl:1
	v_pk_mul_f32 v[218:219], v[218:219], v[54:55]
	v_pk_mul_f32 v[220:221], v[220:221], v[56:57]
	v_perm_b32 v236, v166, v216, v125
	v_perm_b32 v237, v167, v217, v125
	global_store_dword v126, v236, s[16:17] offset:32
	global_store_dword v127, v237, s[16:17] offset:32
	v_pk_mul_f32 v[218:219], v[218:219], v[148:149]
	v_pk_mul_f32 v[220:221], v[220:221], v[150:151]
	v_pk_add_f32 v[50:51], v[50:51], v[52:53]
	v_cvt_pk_bf16_f32 v54, v218, v219
	v_cvt_pk_bf16_f32 v55, v220, v221
	v_add_f32_e32 v153, v50, v51
	v_lshlrev_b32_e32 v218, 16, v54
	v_mov_b32_dpp v166, v54 quad_perm:[1,0,3,2] row_mask:0xf bank_mask:0xf bound_ctrl:1
	v_and_b32_e32 v219, s21, v54
	v_mov_b32_dpp v167, v55 quad_perm:[1,0,3,2] row_mask:0xf bank_mask:0xf bound_ctrl:1
	v_lshlrev_b32_e32 v220, 16, v55
	v_and_b32_e32 v221, s21, v55
	v_perm_b32 v238, v166, v54, v125
	v_perm_b32 v239, v167, v55, v125
	global_store_dword v126, v238, s[18:19] offset:32
	global_store_dword v127, v239, s[18:19] offset:32
	s_add_u32 s16, s16, 0x10000
	s_addc_u32 s17, s17, 0
	s_add_u32 s18, s18, 0x10000
	s_addc_u32 s19, s19, 0
	v_fma_f32 v244, v218, v223, v219
	v_fma_f32 v245, v221, v224, v220
	v_fma_f32 v244, v244, v224, v220
	v_fma_f32 v245, v245, v223, v219
	v_fma_f32 v244, v244, v225, v221
	v_fma_f32 v245, v245, v222, v218
	ds_bpermute_b32 v240, v129, v153
	v_cndmask_b32_e64 v170, v245, v244, s[30:31]
	v_exp_f32_e32 v242, v153
	ds_bpermute_b32 v241, v129, v170
	s_waitcnt lgkmcnt(2)
; #define LAS __attribute__((address_space(3)))
; __device__ __forceinline__ void p_rg_fused(const Frame& F0, const bf16* URAW, int L, const float* cw, const float* cbias, const bf16* Wg, const float* ba, const float* bx, const float* spt,
;                                            bf16* LA, bf16* INP, float* HEND, float* PROD) {
;     ...
;                 for (int m = 0; m < 8; ++m) {
;                     float lr[4], xr[4], ea[4]; unsigned lwv[4], xwv[4];
;                     int gq = g; asm volatile("" : "+v"(gq));
;                     {
;                         f32x4 u4;
; #pragma unroll
;                         for (int e = 0; e < 4; ++e) u4[e] = bf2f(*(const LAS bf16*)(ut + (16 * m + 4 * gq + e) * RGF_PITCH + cl * 2));
;                         const f32x4 na = acc[m][np], nb2 = acc[m][2 + np]; f32x4 e1, e2;
; #pragma unroll
;                         for (int e = 0; e < 4; ++e) { e1[e] = fexp2_(fminf(na[e], 115.f)); e2[e] = fexp2_(fminf(nb2[e], 115.f)); }
;                         const f32x4 d1 = e1 + 1.0f, d2 = e2 + 1.0f, dp = d1 * d2; f32x4 rc;
; #pragma unroll
;                         for (int e = 0; e < 4; ++e) rc[e] = frcp_(dp[e]);
;                         const f32x4 l4 = (d2 * rc) * psp, ig = d1 * rc;
;                         const unsigned lw01 = pk2(l4[0], l4[1]), lw23 = pk2(l4[2], l4[3]);
;                         lr[0] = bflo(lw01); lr[1] = bfhi(lw01); lr[2] = bflo(lw23); lr[3] = bfhi(lw23);
;                         f32x4 ea4, sq;
; #pragma unroll
;                         for (int e = 0; e < 4; ++e) { ea4[e] = fexp2_(lr[e]); ea[e] = ea4[e]; }
; #pragma unroll
;                         for (int e = 0; e < 4; ++e) sq[e] = fsqrt_(__builtin_fabsf(__builtin_fmaf(-ea4[e], ea4[e], 1.0f)));
;                         const f32x4 x4 = sq * ig * u4;
;                         const unsigned xw01 = pk2(x4[0], x4[1]), xw23 = pk2(x4[2], x4[3]);
;                         xr[0] = bflo(xw01); xr[1] = bfhi(xw01); xr[2] = bflo(xw23); xr[3] = bfhi(xw23);
;                         lwv[0] = lw01 & 0xffffu; lwv[1] = lw01 >> 16; lwv[2] = lw23 & 0xffffu; lwv[3] = lw23 >> 16;
;                         xwv[0] = xw01 & 0xffffu; xwv[1] = xw01 >> 16; xwv[2] = xw23 & 0xffffu; xwv[3] = xw23 >> 16; }
; #pragma unroll
;                     for (int ep = 0; ep < 2; ++ep) { const bool odd = (Lq & 1) != 0; const int tok = 16 * m + 4 * gq + 2 * ep + (odd ? 1 : 0);
	v_exp_f32_e32 v213, v210
	v_fma_f32 v215, v211, v212, v169
	v_add_f32_e32 v152, v152, v210
	v_fma_f32 v214, v169, v213, v211
	v_cndmask_b32_e64 v169, v215, v214, s[38:39]
	ds_read_u16_d16_hi v148, v123 offset:25376
	ds_read_u16_d16_hi v149, v123 offset:25904
	ds_read_u16_d16_hi v150, v123 offset:26432
	ds_read_u16_d16_hi v151, v123 offset:26960
	v_min_f32_e32 v46, s20, v46
	v_min_f32_e32 v47, s20, v47
	v_min_f32_e32 v48, s20, v48
	v_min_f32_e32 v49, s20, v49
	v_min_f32_e32 v42, s20, v42
	v_min_f32_e32 v43, s20, v43
	v_min_f32_e32 v44, s20, v44
	v_min_f32_e32 v45, s20, v45
	v_exp_f32_e32 v46, v46
	v_exp_f32_e32 v47, v47
	v_exp_f32_e32 v48, v48
	v_exp_f32_e32 v49, v49
	v_exp_f32_e32 v42, v42
	v_exp_f32_e32 v43, v43
	v_exp_f32_e32 v44, v44
	v_exp_f32_e32 v45, v45
	v_pk_add_f32 v[46:47], v[46:47], 1.0 op_sel_hi:[1,0]
	v_pk_add_f32 v[48:49], v[48:49], 1.0 op_sel_hi:[1,0]
	v_pk_add_f32 v[42:43], v[42:43], 1.0 op_sel_hi:[1,0]
	v_pk_add_f32 v[44:45], v[44:45], 1.0 op_sel_hi:[1,0]
	v_pk_mul_f32 v[178:179], v[46:47], v[42:43]
	v_pk_mul_f32 v[180:181], v[48:49], v[44:45]
	v_rcp_f32_e32 v178, v178
	v_rcp_f32_e32 v179, v179
	v_rcp_f32_e32 v180, v180
	v_rcp_f32_e32 v181, v181
	v_pk_mul_f32 v[42:43], v[42:43], v[178:179]
	v_pk_mul_f32 v[44:45], v[44:45], v[180:181]
	v_pk_mul_f32 v[46:47], v[46:47], v[178:179]
	v_pk_mul_f32 v[48:49], v[48:49], v[180:181]
	v_pk_mul_f32 v[42:43], v[42:43], v[158:159] op_sel_hi:[1,0]
	v_pk_mul_f32 v[44:45], v[44:45], v[158:159] op_sel_hi:[1,0]
	v_cvt_pk_bf16_f32 v178, v42, v43
	v_cvt_pk_bf16_f32 v179, v44, v45
	v_lshlrev_b32_e32 v42, 16, v178
	v_lshlrev_b32_e32 v43, 16, v179
	v_and_b32_e32 v44, s21, v178
	v_and_b32_e32 v45, s21, v179
	v_exp_f32_e32 v184, v42
	v_exp_f32_e32 v185, v44
	v_exp_f32_e32 v186, v43
	v_exp_f32_e32 v187, v45
	s_waitcnt lgkmcnt(4)
	v_exp_f32_e32 v243, v240
	v_fma_f32 v245, v241, v242, v170
	v_add_f32_e32 v153, v153, v240
	v_fma_f32 v244, v170, v243, v241
	v_cndmask_b32_e64 v170, v245, v244, s[40:41]
	ds_bpermute_b32 v240, v177, v153
	v_exp_f32_e32 v242, v153
	ds_bpermute_b32 v241, v177, v170
	v_fma_f32 v180, -v184, v184, 1.0
	v_fma_f32 v181, -v185, v185, 1.0
	v_fma_f32 v182, -v186, v186, 1.0
	v_fma_f32 v183, -v187, v187, 1.0
	v_sqrt_f32_e64 v180, |v180|
	v_sqrt_f32_e64 v181, |v181|
	v_sqrt_f32_e64 v182, |v182|
	v_sqrt_f32_e64 v183, |v183|
	v_mov_b32_dpp v188, v178 quad_perm:[1,0,3,2] row_mask:0xf bank_mask:0xf bound_ctrl:1
	v_mov_b32_dpp v165, v179 quad_perm:[1,0,3,2] row_mask:0xf bank_mask:0xf bound_ctrl:1
	v_pk_mul_f32 v[180:181], v[180:181], v[46:47]
	v_pk_mul_f32 v[182:183], v[182:183], v[48:49]
	v_perm_b32 v206, v188, v178, v125
	v_perm_b32 v207, v165, v179, v125
	global_store_dword v126, v206, s[16:17] offset:32
	global_store_dword v127, v207, s[16:17] offset:32
	v_pk_mul_f32 v[180:181], v[180:181], v[144:145]
	v_pk_mul_f32 v[182:183], v[182:183], v[146:147]
	v_pk_add_f32 v[42:43], v[42:43], v[44:45]
	v_cvt_pk_bf16_f32 v46, v180, v181
	v_cvt_pk_bf16_f32 v47, v182, v183
	v_add_f32_e32 v154, v42, v43
	v_lshlrev_b32_e32 v180, 16, v46
	v_mov_b32_dpp v188, v46 quad_perm:[1,0,3,2] row_mask:0xf bank_mask:0xf bound_ctrl:1
	v_and_b32_e32 v181, s21, v46
	v_mov_b32_dpp v165, v47 quad_perm:[1,0,3,2] row_mask:0xf bank_mask:0xf bound_ctrl:1
	v_lshlrev_b32_e32 v182, 16, v47
	v_and_b32_e32 v183, s21, v47
	v_perm_b32 v208, v188, v46, v125
	v_perm_b32 v209, v165, v47, v125
	global_store_dword v126, v208, s[18:19] offset:32
	global_store_dword v127, v209, s[18:19] offset:32
	s_add_u32 s16, s16, 0x10000
	s_addc_u32 s17, s17, 0
	s_add_u32 s18, s18, 0x10000
	s_addc_u32 s19, s19, 0
	v_fma_f32 v214, v180, v185, v181
	v_fma_f32 v215, v183, v186, v182
	v_fma_f32 v214, v214, v186, v182
	v_fma_f32 v215, v215, v185, v181
	v_fma_f32 v214, v214, v187, v183
	v_fma_f32 v215, v215, v184, v180
	ds_bpermute_b32 v210, v129, v154
	v_cndmask_b32_e64 v171, v215, v214, s[30:31]
	v_exp_f32_e32 v212, v154
	ds_bpermute_b32 v211, v129, v171
	s_waitcnt lgkmcnt(2)
	v_exp_f32_e32 v243, v240
	v_fma_f32 v245, v241, v242, v170
	v_add_f32_e32 v153, v153, v240
	v_fma_f32 v244, v170, v243, v241
	v_cndmask_b32_e64 v170, v245, v244, s[38:39]
	ds_read_u16_d16_hi v144, v123 offset:33824
	ds_read_u16_d16_hi v145, v123 offset:34352
	ds_read_u16_d16_hi v146, v123 offset:34880
	ds_read_u16_d16_hi v147, v123 offset:35408
	v_min_f32_e32 v38, s20, v38
	v_min_f32_e32 v39, s20, v39
	v_min_f32_e32 v40, s20, v40
	v_min_f32_e32 v41, s20, v41
	v_min_f32_e32 v34, s20, v34
	v_min_f32_e32 v35, s20, v35
	v_min_f32_e32 v36, s20, v36
	v_min_f32_e32 v37, s20, v37
	v_exp_f32_e32 v38, v38
	v_exp_f32_e32 v39, v39
	v_exp_f32_e32 v40, v40
	v_exp_f32_e32 v41, v41
	v_exp_f32_e32 v34, v34
	v_exp_f32_e32 v35, v35
	v_exp_f32_e32 v36, v36
	v_exp_f32_e32 v37, v37
	v_pk_add_f32 v[38:39], v[38:39], 1.0 op_sel_hi:[1,0]
	v_pk_add_f32 v[40:41], v[40:41], 1.0 op_sel_hi:[1,0]
	v_pk_add_f32 v[34:35], v[34:35], 1.0 op_sel_hi:[1,0]
	v_pk_add_f32 v[36:37], v[36:37], 1.0 op_sel_hi:[1,0]
	v_pk_mul_f32 v[216:217], v[38:39], v[34:35]
	v_pk_mul_f32 v[218:219], v[40:41], v[36:37]
	v_rcp_f32_e32 v216, v216
	v_rcp_f32_e32 v217, v217
	v_rcp_f32_e32 v218, v218
	v_rcp_f32_e32 v219, v219
	v_pk_mul_f32 v[34:35], v[34:35], v[216:217]
	v_pk_mul_f32 v[36:37], v[36:37], v[218:219]
	v_pk_mul_f32 v[38:39], v[38:39], v[216:217]
	v_pk_mul_f32 v[40:41], v[40:41], v[218:219]
	v_pk_mul_f32 v[34:35], v[34:35], v[158:159] op_sel_hi:[1,0]
	v_pk_mul_f32 v[36:37], v[36:37], v[158:159] op_sel_hi:[1,0]
	v_cvt_pk_bf16_f32 v216, v34, v35
	v_cvt_pk_bf16_f32 v217, v36, v37
	v_lshlrev_b32_e32 v34, 16, v216
	v_lshlrev_b32_e32 v35, 16, v217
	v_and_b32_e32 v36, s21, v216
	v_and_b32_e32 v37, s21, v217
	v_exp_f32_e32 v222, v34
	v_exp_f32_e32 v223, v36
	v_exp_f32_e32 v224, v35
	v_exp_f32_e32 v225, v37
	s_waitcnt lgkmcnt(4)
; #define LAS __attribute__((address_space(3)))
; __device__ __forceinline__ void p_rg_fused(const Frame& F0, const bf16* URAW, int L, const float* cw, const float* cbias, const bf16* Wg, const float* ba, const float* bx, const float* spt,
;                                            bf16* LA, bf16* INP, float* HEND, float* PROD) {
;     ...
;                 for (int m = 0; m < 8; ++m) {
;                     float lr[4], xr[4], ea[4]; unsigned lwv[4], xwv[4];
;                     int gq = g; asm volatile("" : "+v"(gq));
;                     {
;                         f32x4 u4;
; #pragma unroll
;                         for (int e = 0; e < 4; ++e) u4[e] = bf2f(*(const LAS bf16*)(ut + (16 * m + 4 * gq + e) * RGF_PITCH + cl * 2));
;                         const f32x4 na = acc[m][np], nb2 = acc[m][2 + np]; f32x4 e1, e2;
; #pragma unroll
;                         for (int e = 0; e < 4; ++e) { e1[e] = fexp2_(fminf(na[e], 115.f)); e2[e] = fexp2_(fminf(nb2[e], 115.f)); }
;                         const f32x4 d1 = e1 + 1.0f, d2 = e2 + 1.0f, dp = d1 * d2; f32x4 rc;
; #pragma unroll
;                         for (int e = 0; e < 4; ++e) rc[e] = frcp_(dp[e]);
;                         const f32x4 l4 = (d2 * rc) * psp, ig = d1 * rc;
;                         const unsigned lw01 = pk2(l4[0], l4[1]), lw23 = pk2(l4[2], l4[3]);
;                         lr[0] = bflo(lw01); lr[1] = bfhi(lw01); lr[2] = bflo(lw23); lr[3] = bfhi(lw23);
;                         f32x4 ea4, sq;
; #pragma unroll
;                         for (int e = 0; e < 4; ++e) { ea4[e] = fexp2_(lr[e]); ea[e] = ea4[e]; }
; #pragma unroll
;                         for (int e = 0; e < 4; ++e) sq[e] = fsqrt_(__builtin_fabsf(__builtin_fmaf(-ea4[e], ea4[e], 1.0f)));
;                         const f32x4 x4 = sq * ig * u4;
;                         const unsigned xw01 = pk2(x4[0], x4[1]), xw23 = pk2(x4[2], x4[3]);
;                         xr[0] = bflo(xw01); xr[1] = bfhi(xw01); xr[2] = bflo(xw23); xr[3] = bfhi(xw23);
;                         lwv[0] = lw01 & 0xffffu; lwv[1] = lw01 >> 16; lwv[2] = lw23 & 0xffffu; lwv[3] = lw23 >> 16;
;                         xwv[0] = xw01 & 0xffffu; xwv[1] = xw01 >> 16; xwv[2] = xw23 & 0xffffu; xwv[3] = xw23 >> 16; }
; #pragma unroll
;                     for (int ep = 0; ep < 2; ++ep) { const bool odd = (Lq & 1) != 0; const int tok = 16 * m + 4 * gq + 2 * ep + (odd ? 1 : 0);
	v_exp_f32_e32 v213, v210
	v_fma_f32 v215, v211, v212, v171
	v_add_f32_e32 v154, v154, v210
	v_fma_f32 v214, v171, v213, v211
	v_cndmask_b32_e64 v171, v215, v214, s[40:41]
	ds_bpermute_b32 v210, v177, v154
	v_exp_f32_e32 v212, v154
	ds_bpermute_b32 v211, v177, v171
	v_fma_f32 v218, -v222, v222, 1.0
	v_fma_f32 v219, -v223, v223, 1.0
	v_fma_f32 v220, -v224, v224, 1.0
	v_fma_f32 v221, -v225, v225, 1.0
	v_sqrt_f32_e64 v218, |v218|
	v_sqrt_f32_e64 v219, |v219|
	v_sqrt_f32_e64 v220, |v220|
	v_sqrt_f32_e64 v221, |v221|
	v_mov_b32_dpp v166, v216 quad_perm:[1,0,3,2] row_mask:0xf bank_mask:0xf bound_ctrl:1
	v_mov_b32_dpp v167, v217 quad_perm:[1,0,3,2] row_mask:0xf bank_mask:0xf bound_ctrl:1
	v_pk_mul_f32 v[218:219], v[218:219], v[38:39]
	v_pk_mul_f32 v[220:221], v[220:221], v[40:41]
	v_perm_b32 v236, v166, v216, v125
	v_perm_b32 v237, v167, v217, v125
	global_store_dword v126, v236, s[16:17] offset:32
	global_store_dword v127, v237, s[16:17] offset:32
	v_pk_mul_f32 v[218:219], v[218:219], v[148:149]
	v_pk_mul_f32 v[220:221], v[220:221], v[150:151]
	v_pk_add_f32 v[34:35], v[34:35], v[36:37]
	v_cvt_pk_bf16_f32 v38, v218, v219
	v_cvt_pk_bf16_f32 v39, v220, v221
	v_add_f32_e32 v155, v34, v35
	v_lshlrev_b32_e32 v218, 16, v38
	v_mov_b32_dpp v166, v38 quad_perm:[1,0,3,2] row_mask:0xf bank_mask:0xf bound_ctrl:1
	v_and_b32_e32 v219, s21, v38
	v_mov_b32_dpp v167, v39 quad_perm:[1,0,3,2] row_mask:0xf bank_mask:0xf bound_ctrl:1
	v_lshlrev_b32_e32 v220, 16, v39
	v_and_b32_e32 v221, s21, v39
	v_perm_b32 v238, v166, v38, v125
	v_perm_b32 v239, v167, v39, v125
	global_store_dword v126, v238, s[18:19] offset:32
	global_store_dword v127, v239, s[18:19] offset:32
	s_add_u32 s16, s16, 0x10000
	s_addc_u32 s17, s17, 0
	s_add_u32 s18, s18, 0x10000
	s_addc_u32 s19, s19, 0
	v_fma_f32 v244, v218, v223, v219
	v_fma_f32 v245, v221, v224, v220
	v_fma_f32 v244, v244, v224, v220
	v_fma_f32 v245, v245, v223, v219
	v_fma_f32 v244, v244, v225, v221
	v_fma_f32 v245, v245, v222, v218
	ds_bpermute_b32 v240, v129, v155
	v_cndmask_b32_e64 v172, v245, v244, s[30:31]
	v_exp_f32_e32 v242, v155
	ds_bpermute_b32 v241, v129, v172
	s_waitcnt lgkmcnt(2)
	v_exp_f32_e32 v213, v210
	v_fma_f32 v215, v211, v212, v171
	v_add_f32_e32 v154, v154, v210
	v_fma_f32 v214, v171, v213, v211
	v_cndmask_b32_e64 v171, v215, v214, s[38:39]
	ds_read_u16_d16_hi v148, v123 offset:42272
	ds_read_u16_d16_hi v149, v123 offset:42800
	ds_read_u16_d16_hi v150, v123 offset:43328
	ds_read_u16_d16_hi v151, v123 offset:43856
	v_min_f32_e32 v30, s20, v30
	v_min_f32_e32 v31, s20, v31
	v_min_f32_e32 v32, s20, v32
	v_min_f32_e32 v33, s20, v33
	v_min_f32_e32 v26, s20, v26
	v_min_f32_e32 v27, s20, v27
	v_min_f32_e32 v28, s20, v28
	v_min_f32_e32 v29, s20, v29
	v_exp_f32_e32 v30, v30
	v_exp_f32_e32 v31, v31
	v_exp_f32_e32 v32, v32
	v_exp_f32_e32 v33, v33
	v_exp_f32_e32 v26, v26
	v_exp_f32_e32 v27, v27
	v_exp_f32_e32 v28, v28
	v_exp_f32_e32 v29, v29
	v_pk_add_f32 v[30:31], v[30:31], 1.0 op_sel_hi:[1,0]
	v_pk_add_f32 v[32:33], v[32:33], 1.0 op_sel_hi:[1,0]
	v_pk_add_f32 v[26:27], v[26:27], 1.0 op_sel_hi:[1,0]
	v_pk_add_f32 v[28:29], v[28:29], 1.0 op_sel_hi:[1,0]
	v_pk_mul_f32 v[178:179], v[30:31], v[26:27]
	v_pk_mul_f32 v[180:181], v[32:33], v[28:29]
	v_rcp_f32_e32 v178, v178
	v_rcp_f32_e32 v179, v179
	v_rcp_f32_e32 v180, v180
	v_rcp_f32_e32 v181, v181
	v_pk_mul_f32 v[26:27], v[26:27], v[178:179]
	v_pk_mul_f32 v[28:29], v[28:29], v[180:181]
	v_pk_mul_f32 v[30:31], v[30:31], v[178:179]
	v_pk_mul_f32 v[32:33], v[32:33], v[180:181]
	v_pk_mul_f32 v[26:27], v[26:27], v[158:159] op_sel_hi:[1,0]
	v_pk_mul_f32 v[28:29], v[28:29], v[158:159] op_sel_hi:[1,0]
	v_cvt_pk_bf16_f32 v178, v26, v27
	v_cvt_pk_bf16_f32 v179, v28, v29
	v_lshlrev_b32_e32 v26, 16, v178
	v_lshlrev_b32_e32 v27, 16, v179
	v_and_b32_e32 v28, s21, v178
	v_and_b32_e32 v29, s21, v179
	v_exp_f32_e32 v184, v26
	v_exp_f32_e32 v185, v28
	v_exp_f32_e32 v186, v27
	v_exp_f32_e32 v187, v29
	s_waitcnt lgkmcnt(4)
	v_exp_f32_e32 v243, v240
	v_fma_f32 v245, v241, v242, v172
	v_add_f32_e32 v155, v155, v240
	v_fma_f32 v244, v172, v243, v241
	v_cndmask_b32_e64 v172, v245, v244, s[40:41]
	ds_bpermute_b32 v240, v177, v155
	v_exp_f32_e32 v242, v155
	ds_bpermute_b32 v241, v177, v172
	v_fma_f32 v180, -v184, v184, 1.0
	v_fma_f32 v181, -v185, v185, 1.0
	v_fma_f32 v182, -v186, v186, 1.0
	v_fma_f32 v183, -v187, v187, 1.0
	v_sqrt_f32_e64 v180, |v180|
	v_sqrt_f32_e64 v181, |v181|
	v_sqrt_f32_e64 v182, |v182|
	v_sqrt_f32_e64 v183, |v183|
	v_mov_b32_dpp v188, v178 quad_perm:[1,0,3,2] row_mask:0xf bank_mask:0xf bound_ctrl:1
	v_mov_b32_dpp v165, v179 quad_perm:[1,0,3,2] row_mask:0xf bank_mask:0xf bound_ctrl:1
	v_pk_mul_f32 v[180:181], v[180:181], v[30:31]
	v_pk_mul_f32 v[182:183], v[182:183], v[32:33]
	v_perm_b32 v206, v188, v178, v125
	v_perm_b32 v207, v165, v179, v125
	global_store_dword v126, v206, s[16:17] offset:32
	global_store_dword v127, v207, s[16:17] offset:32
	v_pk_mul_f32 v[180:181], v[180:181], v[144:145]
	v_pk_mul_f32 v[182:183], v[182:183], v[146:147]
	v_pk_add_f32 v[26:27], v[26:27], v[28:29]
	v_cvt_pk_bf16_f32 v30, v180, v181
	v_cvt_pk_bf16_f32 v31, v182, v183
	v_add_f32_e32 v156, v26, v27
	v_lshlrev_b32_e32 v180, 16, v30
	v_mov_b32_dpp v188, v30 quad_perm:[1,0,3,2] row_mask:0xf bank_mask:0xf bound_ctrl:1
	v_and_b32_e32 v181, s21, v30
	v_mov_b32_dpp v165, v31 quad_perm:[1,0,3,2] row_mask:0xf bank_mask:0xf bound_ctrl:1
	v_lshlrev_b32_e32 v182, 16, v31
	v_and_b32_e32 v183, s21, v31
	v_perm_b32 v208, v188, v30, v125
	v_perm_b32 v209, v165, v31, v125
	global_store_dword v126, v208, s[18:19] offset:32
	global_store_dword v127, v209, s[18:19] offset:32
	s_add_u32 s16, s16, 0x10000
	s_addc_u32 s17, s17, 0
	s_add_u32 s18, s18, 0x10000
	s_addc_u32 s19, s19, 0
	v_fma_f32 v214, v180, v185, v181
	v_fma_f32 v215, v183, v186, v182
	v_fma_f32 v214, v214, v186, v182
	v_fma_f32 v215, v215, v185, v181
	v_fma_f32 v214, v214, v187, v183
	v_fma_f32 v215, v215, v184, v180
	ds_bpermute_b32 v210, v129, v156
	v_cndmask_b32_e64 v173, v215, v214, s[30:31]
	v_exp_f32_e32 v212, v156
	ds_bpermute_b32 v211, v129, v173
	s_waitcnt lgkmcnt(2)
; #define LAS __attribute__((address_space(3)))
; __device__ __forceinline__ void p_rg_fused(const Frame& F0, const bf16* URAW, int L, const float* cw, const float* cbias, const bf16* Wg, const float* ba, const float* bx, const float* spt,
;                                            bf16* LA, bf16* INP, float* HEND, float* PROD) {
;     ...
;                 for (int m = 0; m < 8; ++m) {
;                     float lr[4], xr[4], ea[4]; unsigned lwv[4], xwv[4];
;                     int gq = g; asm volatile("" : "+v"(gq));
;                     {
;                         f32x4 u4;
; #pragma unroll
;                         for (int e = 0; e < 4; ++e) u4[e] = bf2f(*(const LAS bf16*)(ut + (16 * m + 4 * gq + e) * RGF_PITCH + cl * 2));
;                         const f32x4 na = acc[m][np], nb2 = acc[m][2 + np]; f32x4 e1, e2;
; #pragma unroll
;                         for (int e = 0; e < 4; ++e) { e1[e] = fexp2_(fminf(na[e], 115.f)); e2[e] = fexp2_(fminf(nb2[e], 115.f)); }
;                         const f32x4 d1 = e1 + 1.0f, d2 = e2 + 1.0f, dp = d1 * d2; f32x4 rc;
; #pragma unroll
;                         for (int e = 0; e < 4; ++e) rc[e] = frcp_(dp[e]);
;                         const f32x4 l4 = (d2 * rc) * psp, ig = d1 * rc;
;                         const unsigned lw01 = pk2(l4[0], l4[1]), lw23 = pk2(l4[2], l4[3]);
;                         lr[0] = bflo(lw01); lr[1] = bfhi(lw01); lr[2] = bflo(lw23); lr[3] = bfhi(lw23);
;                         f32x4 ea4, sq;
; #pragma unroll
;                         for (int e = 0; e < 4; ++e) { ea4[e] = fexp2_(lr[e]); ea[e] = ea4[e]; }
; #pragma unroll
;                         for (int e = 0; e < 4; ++e) sq[e] = fsqrt_(__builtin_fabsf(__builtin_fmaf(-ea4[e], ea4[e], 1.0f)));
;                         const f32x4 x4 = sq * ig * u4;
;                         const unsigned xw01 = pk2(x4[0], x4[1]), xw23 = pk2(x4[2], x4[3]);
;                         xr[0] = bflo(xw01); xr[1] = bfhi(xw01); xr[2] = bflo(xw23); xr[3] = bfhi(xw23);
;                         lwv[0] = lw01 & 0xffffu; lwv[1] = lw01 >> 16; lwv[2] = lw23 & 0xffffu; lwv[3] = lw23 >> 16;
;                         xwv[0] = xw01 & 0xffffu; xwv[1] = xw01 >> 16; xwv[2] = xw23 & 0xffffu; xwv[3] = xw23 >> 16; }
; #pragma unroll
;                     for (int ep = 0; ep < 2; ++ep) { const bool odd = (Lq & 1) != 0; const int tok = 16 * m + 4 * gq + 2 * ep + (odd ? 1 : 0);
	v_exp_f32_e32 v243, v240
	v_fma_f32 v245, v241, v242, v172
	v_add_f32_e32 v155, v155, v240
	v_fma_f32 v244, v172, v243, v241
	v_cndmask_b32_e64 v172, v245, v244, s[38:39]
	ds_read_u16_d16_hi v144, v123 offset:50720
	ds_read_u16_d16_hi v145, v123 offset:51248
	ds_read_u16_d16_hi v146, v123 offset:51776
	ds_read_u16_d16_hi v147, v123 offset:52304
	v_min_f32_e32 v22, s20, v22
	v_min_f32_e32 v23, s20, v23
	v_min_f32_e32 v24, s20, v24
	v_min_f32_e32 v25, s20, v25
	v_min_f32_e32 v18, s20, v18
	v_min_f32_e32 v19, s20, v19
	v_min_f32_e32 v20, s20, v20
	v_min_f32_e32 v21, s20, v21
	v_exp_f32_e32 v22, v22
	v_exp_f32_e32 v23, v23
	v_exp_f32_e32 v24, v24
	v_exp_f32_e32 v25, v25
	v_exp_f32_e32 v18, v18
	v_exp_f32_e32 v19, v19
	v_exp_f32_e32 v20, v20
	v_exp_f32_e32 v21, v21
	v_pk_add_f32 v[22:23], v[22:23], 1.0 op_sel_hi:[1,0]
	v_pk_add_f32 v[24:25], v[24:25], 1.0 op_sel_hi:[1,0]
	v_pk_add_f32 v[18:19], v[18:19], 1.0 op_sel_hi:[1,0]
	v_pk_add_f32 v[20:21], v[20:21], 1.0 op_sel_hi:[1,0]
	v_pk_mul_f32 v[216:217], v[22:23], v[18:19]
	v_pk_mul_f32 v[218:219], v[24:25], v[20:21]
	v_rcp_f32_e32 v216, v216
	v_rcp_f32_e32 v217, v217
	v_rcp_f32_e32 v218, v218
	v_rcp_f32_e32 v219, v219
	v_pk_mul_f32 v[18:19], v[18:19], v[216:217]
	v_pk_mul_f32 v[20:21], v[20:21], v[218:219]
	v_pk_mul_f32 v[22:23], v[22:23], v[216:217]
	v_pk_mul_f32 v[24:25], v[24:25], v[218:219]
	v_pk_mul_f32 v[18:19], v[18:19], v[158:159] op_sel_hi:[1,0]
	v_pk_mul_f32 v[20:21], v[20:21], v[158:159] op_sel_hi:[1,0]
	v_cvt_pk_bf16_f32 v216, v18, v19
	v_cvt_pk_bf16_f32 v217, v20, v21
	v_lshlrev_b32_e32 v18, 16, v216
	v_lshlrev_b32_e32 v19, 16, v217
	v_and_b32_e32 v20, s21, v216
	v_and_b32_e32 v21, s21, v217
	v_exp_f32_e32 v222, v18
	v_exp_f32_e32 v223, v20
	v_exp_f32_e32 v224, v19
	v_exp_f32_e32 v225, v21
	s_waitcnt lgkmcnt(4)
	v_exp_f32_e32 v213, v210
	v_fma_f32 v215, v211, v212, v173
	v_add_f32_e32 v156, v156, v210
	v_fma_f32 v214, v173, v213, v211
	v_cndmask_b32_e64 v173, v215, v214, s[40:41]
	ds_bpermute_b32 v210, v177, v156
	v_exp_f32_e32 v212, v156
	ds_bpermute_b32 v211, v177, v173
	v_fma_f32 v218, -v222, v222, 1.0
	v_fma_f32 v219, -v223, v223, 1.0
	v_fma_f32 v220, -v224, v224, 1.0
	v_fma_f32 v221, -v225, v225, 1.0
	v_sqrt_f32_e64 v218, |v218|
	v_sqrt_f32_e64 v219, |v219|
	v_sqrt_f32_e64 v220, |v220|
	v_sqrt_f32_e64 v221, |v221|
	v_mov_b32_dpp v166, v216 quad_perm:[1,0,3,2] row_mask:0xf bank_mask:0xf bound_ctrl:1
	v_mov_b32_dpp v167, v217 quad_perm:[1,0,3,2] row_mask:0xf bank_mask:0xf bound_ctrl:1
	v_pk_mul_f32 v[218:219], v[218:219], v[22:23]
	v_pk_mul_f32 v[220:221], v[220:221], v[24:25]
	v_perm_b32 v236, v166, v216, v125
	v_perm_b32 v237, v167, v217, v125
	global_store_dword v126, v236, s[16:17] offset:32
	global_store_dword v127, v237, s[16:17] offset:32
	v_pk_mul_f32 v[218:219], v[218:219], v[148:149]
	v_pk_mul_f32 v[220:221], v[220:221], v[150:151]
	v_pk_add_f32 v[18:19], v[18:19], v[20:21]
	v_cvt_pk_bf16_f32 v22, v218, v219
	v_cvt_pk_bf16_f32 v23, v220, v221
	v_add_f32_e32 v157, v18, v19
	v_lshlrev_b32_e32 v218, 16, v22
	v_mov_b32_dpp v166, v22 quad_perm:[1,0,3,2] row_mask:0xf bank_mask:0xf bound_ctrl:1
	v_and_b32_e32 v219, s21, v22
	v_mov_b32_dpp v167, v23 quad_perm:[1,0,3,2] row_mask:0xf bank_mask:0xf bound_ctrl:1
	v_lshlrev_b32_e32 v220, 16, v23
	v_and_b32_e32 v221, s21, v23
	v_perm_b32 v238, v166, v22, v125
	v_perm_b32 v239, v167, v23, v125
	global_store_dword v126, v238, s[18:19] offset:32
	global_store_dword v127, v239, s[18:19] offset:32
	s_add_u32 s16, s16, 0x10000
	s_addc_u32 s17, s17, 0
	s_add_u32 s18, s18, 0x10000
	s_addc_u32 s19, s19, 0
	v_fma_f32 v244, v218, v223, v219
	v_fma_f32 v245, v221, v224, v220
	v_fma_f32 v244, v244, v224, v220
	v_fma_f32 v245, v245, v223, v219
	v_fma_f32 v244, v244, v225, v221
	v_fma_f32 v245, v245, v222, v218
	ds_bpermute_b32 v240, v129, v157
	v_cndmask_b32_e64 v174, v245, v244, s[30:31]
	v_exp_f32_e32 v242, v157
	ds_bpermute_b32 v241, v129, v174
	s_waitcnt lgkmcnt(2)
	v_exp_f32_e32 v213, v210
	v_fma_f32 v215, v211, v212, v173
	v_add_f32_e32 v156, v156, v210
	v_fma_f32 v214, v173, v213, v211
	v_cndmask_b32_e64 v173, v215, v214, s[38:39]
	ds_read_u16_d16_hi v148, v123 offset:59168
	ds_read_u16_d16_hi v149, v123 offset:59696
	ds_read_u16_d16_hi v150, v123 offset:60224
	ds_read_u16_d16_hi v151, v123 offset:60752
	v_min_f32_e32 v14, s20, v14
	v_min_f32_e32 v15, s20, v15
	v_min_f32_e32 v16, s20, v16
	v_min_f32_e32 v17, s20, v17
	v_min_f32_e32 v10, s20, v10
	v_min_f32_e32 v11, s20, v11
	v_min_f32_e32 v12, s20, v12
	v_min_f32_e32 v13, s20, v13
	v_exp_f32_e32 v14, v14
	v_exp_f32_e32 v15, v15
	v_exp_f32_e32 v16, v16
	v_exp_f32_e32 v17, v17
	v_exp_f32_e32 v10, v10
	v_exp_f32_e32 v11, v11
	v_exp_f32_e32 v12, v12
	v_exp_f32_e32 v13, v13
	v_pk_add_f32 v[14:15], v[14:15], 1.0 op_sel_hi:[1,0]
	v_pk_add_f32 v[16:17], v[16:17], 1.0 op_sel_hi:[1,0]
	v_pk_add_f32 v[10:11], v[10:11], 1.0 op_sel_hi:[1,0]
	v_pk_add_f32 v[12:13], v[12:13], 1.0 op_sel_hi:[1,0]
	v_pk_mul_f32 v[178:179], v[14:15], v[10:11]
	v_pk_mul_f32 v[180:181], v[16:17], v[12:13]
	v_rcp_f32_e32 v178, v178
	v_rcp_f32_e32 v179, v179
	v_rcp_f32_e32 v180, v180
	v_rcp_f32_e32 v181, v181
	v_pk_mul_f32 v[10:11], v[10:11], v[178:179]
	v_pk_mul_f32 v[12:13], v[12:13], v[180:181]
	v_pk_mul_f32 v[14:15], v[14:15], v[178:179]
	v_pk_mul_f32 v[16:17], v[16:17], v[180:181]
	v_pk_mul_f32 v[10:11], v[10:11], v[158:159] op_sel_hi:[1,0]
	v_pk_mul_f32 v[12:13], v[12:13], v[158:159] op_sel_hi:[1,0]
	v_cvt_pk_bf16_f32 v178, v10, v11
	v_cvt_pk_bf16_f32 v179, v12, v13
	v_lshlrev_b32_e32 v10, 16, v178
	v_lshlrev_b32_e32 v11, 16, v179
	v_and_b32_e32 v12, s21, v178
	v_and_b32_e32 v13, s21, v179
	v_exp_f32_e32 v184, v10
	v_exp_f32_e32 v185, v12
	v_exp_f32_e32 v186, v11
	v_exp_f32_e32 v187, v13
	s_waitcnt lgkmcnt(4)
; __device__ __forceinline__ float bflo(unsigned w) { return __uint_as_float(w << 16); }
; __device__ __forceinline__ void p_rg_fused(const Frame& F0, const bf16* URAW, int L, const float* cw, const float* cbias, const bf16* Wg, const float* ba, const float* bx, const float* spt,
;                                            bf16* LA, bf16* INP, float* HEND, float* PROD) {
;     ...
;                         const f32x4 na = acc[m][np], nb2 = acc[m][2 + np]; f32x4 e1, e2;
; #pragma unroll
;                         for (int e = 0; e < 4; ++e) { e1[e] = fexp2_(fminf(na[e], 115.f)); e2[e] = fexp2_(fminf(nb2[e], 115.f)); }
;                         const f32x4 d1 = e1 + 1.0f, d2 = e2 + 1.0f, dp = d1 * d2; f32x4 rc;
; #pragma unroll
;                         for (int e = 0; e < 4; ++e) rc[e] = frcp_(dp[e]);
;                         const f32x4 l4 = (d2 * rc) * psp, ig = d1 * rc;
;                         const unsigned lw01 = pk2(l4[0], l4[1]), lw23 = pk2(l4[2], l4[3]);
;                         lr[0] = bflo(lw01); lr[1] = bfhi(lw01); lr[2] = bflo(lw23); lr[3] = bfhi(lw23);
;                         f32x4 ea4, sq;
; #pragma unroll
;                         for (int e = 0; e < 4; ++e) { ea4[e] = fexp2_(lr[e]); ea[e] = ea4[e]; }
; #pragma unroll
;                         for (int e = 0; e < 4; ++e) sq[e] = fsqrt_(__builtin_fabsf(__builtin_fmaf(-ea4[e], ea4[e], 1.0f)));
;                         const f32x4 x4 = sq * ig * u4;
;                         const unsigned xw01 = pk2(x4[0], x4[1]), xw23 = pk2(x4[2], x4[3]);
;                         xr[0] = bflo(xw01); xr[1] = bfhi(xw01); xr[2] = bflo(xw23); xr[3] = bfhi(xw23);
;                         lwv[0] = lw01 & 0xffffu; lwv[1] = lw01 >> 16; lwv[2] = lw23 & 0xffffu; lwv[3] = lw23 >> 16;
;                         xwv[0] = xw01 & 0xffffu; xwv[1] = xw01 >> 16; xwv[2] = xw23 & 0xffffu; xwv[3] = xw23 >> 16; }
; #pragma unroll
;                     for (int ep = 0; ep < 2; ++ep) { const bool odd = (Lq & 1) != 0; const int tok = 16 * m + 4 * gq + 2 * ep + (odd ? 1 : 0);
;                         const unsigned sl = odd ? lwv[2 * ep] : lwv[2 * ep + 1], sx = odd ? xwv[2 * ep] : xwv[2 * ep + 1];
;                         const unsigned rl = (unsigned)__builtin_amdgcn_update_dpp(0, (int)sl, 0xB1, 0xf, 0xf, true), rx = (unsigned)__builtin_amdgcn_update_dpp(0, (int)sx, 0xB1, 0xf, 0xf, true);
	v_exp_f32_e32 v243, v240
	v_fma_f32 v245, v241, v242, v174
	v_add_f32_e32 v157, v157, v240
	v_fma_f32 v244, v174, v243, v241
	v_cndmask_b32_e64 v174, v245, v244, s[40:41]
	ds_bpermute_b32 v240, v177, v157
	v_exp_f32_e32 v242, v157
	ds_bpermute_b32 v241, v177, v174
	v_fma_f32 v180, -v184, v184, 1.0
	v_fma_f32 v181, -v185, v185, 1.0
	v_fma_f32 v182, -v186, v186, 1.0
	v_fma_f32 v183, -v187, v187, 1.0
	v_sqrt_f32_e64 v180, |v180|
	v_sqrt_f32_e64 v181, |v181|
	v_sqrt_f32_e64 v182, |v182|
	v_sqrt_f32_e64 v183, |v183|
	v_mov_b32_dpp v188, v178 quad_perm:[1,0,3,2] row_mask:0xf bank_mask:0xf bound_ctrl:1
	v_mov_b32_dpp v165, v179 quad_perm:[1,0,3,2] row_mask:0xf bank_mask:0xf bound_ctrl:1
	v_pk_mul_f32 v[180:181], v[180:181], v[14:15]
	v_pk_mul_f32 v[182:183], v[182:183], v[16:17]
	v_perm_b32 v206, v188, v178, v125
	v_perm_b32 v207, v165, v179, v125
	global_store_dword v126, v206, s[16:17] offset:32
	global_store_dword v127, v207, s[16:17] offset:32
	v_pk_mul_f32 v[180:181], v[180:181], v[144:145]
	v_pk_mul_f32 v[182:183], v[182:183], v[146:147]
	v_pk_add_f32 v[10:11], v[10:11], v[12:13]
	v_cvt_pk_bf16_f32 v14, v180, v181
	v_cvt_pk_bf16_f32 v15, v182, v183
	v_add_f32_e32 v246, v10, v11
	v_lshlrev_b32_e32 v180, 16, v14
	v_mov_b32_dpp v188, v14 quad_perm:[1,0,3,2] row_mask:0xf bank_mask:0xf bound_ctrl:1
	v_and_b32_e32 v181, s21, v14
	v_mov_b32_dpp v165, v15 quad_perm:[1,0,3,2] row_mask:0xf bank_mask:0xf bound_ctrl:1
	v_lshlrev_b32_e32 v182, 16, v15
	v_and_b32_e32 v183, s21, v15
	v_perm_b32 v208, v188, v14, v125
	v_perm_b32 v209, v165, v15, v125
	global_store_dword v126, v208, s[18:19] offset:32
	global_store_dword v127, v209, s[18:19] offset:32
	s_add_u32 s16, s16, 0x10000
	s_addc_u32 s17, s17, 0
	s_add_u32 s18, s18, 0x10000
	s_addc_u32 s19, s19, 0
	v_fma_f32 v214, v180, v185, v181
	v_fma_f32 v215, v183, v186, v182
	v_fma_f32 v214, v214, v186, v182
	v_fma_f32 v215, v215, v185, v181
	v_fma_f32 v214, v214, v187, v183
	v_fma_f32 v215, v215, v184, v180
	ds_bpermute_b32 v210, v129, v246
	v_cndmask_b32_e64 v175, v215, v214, s[30:31]
	v_exp_f32_e32 v212, v246
	ds_bpermute_b32 v211, v129, v175
	s_waitcnt lgkmcnt(2)
	v_exp_f32_e32 v243, v240
	v_fma_f32 v245, v241, v242, v174
	v_add_f32_e32 v157, v157, v240
	v_fma_f32 v244, v174, v243, v241
	v_cndmask_b32_e64 v174, v245, v244, s[38:39]
	v_min_f32_e32 v6, s20, v6
	v_min_f32_e32 v7, s20, v7
	v_min_f32_e32 v8, s20, v8
	v_min_f32_e32 v9, s20, v9
	v_min_f32_e32 v2, s20, v2
	v_min_f32_e32 v3, s20, v3
	v_min_f32_e32 v4, s20, v4
	v_min_f32_e32 v5, s20, v5
	v_exp_f32_e32 v6, v6
	v_exp_f32_e32 v7, v7
	v_exp_f32_e32 v8, v8
	v_exp_f32_e32 v9, v9
	v_exp_f32_e32 v2, v2
	v_exp_f32_e32 v3, v3
	v_exp_f32_e32 v4, v4
	v_exp_f32_e32 v5, v5
	v_pk_add_f32 v[6:7], v[6:7], 1.0 op_sel_hi:[1,0]
	v_pk_add_f32 v[8:9], v[8:9], 1.0 op_sel_hi:[1,0]
	v_pk_add_f32 v[2:3], v[2:3], 1.0 op_sel_hi:[1,0]
	v_pk_add_f32 v[4:5], v[4:5], 1.0 op_sel_hi:[1,0]
	v_pk_mul_f32 v[216:217], v[6:7], v[2:3]
	v_pk_mul_f32 v[218:219], v[8:9], v[4:5]
	v_rcp_f32_e32 v216, v216
	v_rcp_f32_e32 v217, v217
	v_rcp_f32_e32 v218, v218
	v_rcp_f32_e32 v219, v219
	v_pk_mul_f32 v[2:3], v[2:3], v[216:217]
	v_pk_mul_f32 v[4:5], v[4:5], v[218:219]
	v_pk_mul_f32 v[6:7], v[6:7], v[216:217]
	v_pk_mul_f32 v[8:9], v[8:9], v[218:219]
	v_pk_mul_f32 v[2:3], v[2:3], v[158:159] op_sel_hi:[1,0]
	v_pk_mul_f32 v[4:5], v[4:5], v[158:159] op_sel_hi:[1,0]
	v_cvt_pk_bf16_f32 v216, v2, v3
	v_cvt_pk_bf16_f32 v217, v4, v5
	v_lshlrev_b32_e32 v2, 16, v216
	v_lshlrev_b32_e32 v3, 16, v217
	v_and_b32_e32 v4, s21, v216
	v_and_b32_e32 v5, s21, v217
	v_exp_f32_e32 v222, v2
	v_exp_f32_e32 v223, v4
	v_exp_f32_e32 v224, v3
	v_exp_f32_e32 v225, v5
	s_waitcnt lgkmcnt(0)
	v_exp_f32_e32 v213, v210
	v_fma_f32 v215, v211, v212, v175
	v_add_f32_e32 v246, v246, v210
	v_fma_f32 v214, v175, v213, v211
	v_cndmask_b32_e64 v175, v215, v214, s[40:41]
	ds_bpermute_b32 v210, v177, v246
	v_exp_f32_e32 v212, v246
	ds_bpermute_b32 v211, v177, v175
	v_fma_f32 v218, -v222, v222, 1.0
	v_fma_f32 v219, -v223, v223, 1.0
	v_fma_f32 v220, -v224, v224, 1.0
	v_fma_f32 v221, -v225, v225, 1.0
	v_sqrt_f32_e64 v218, |v218|
	v_sqrt_f32_e64 v219, |v219|
	v_sqrt_f32_e64 v220, |v220|
	v_sqrt_f32_e64 v221, |v221|
	v_mov_b32_dpp v166, v216 quad_perm:[1,0,3,2] row_mask:0xf bank_mask:0xf bound_ctrl:1
	v_mov_b32_dpp v167, v217 quad_perm:[1,0,3,2] row_mask:0xf bank_mask:0xf bound_ctrl:1
	v_pk_mul_f32 v[218:219], v[218:219], v[6:7]
	v_pk_mul_f32 v[220:221], v[220:221], v[8:9]
	v_perm_b32 v236, v166, v216, v125
	v_perm_b32 v237, v167, v217, v125
	global_store_dword v126, v236, s[16:17] offset:32
	global_store_dword v127, v237, s[16:17] offset:32
	v_pk_mul_f32 v[218:219], v[218:219], v[148:149]
	v_pk_mul_f32 v[220:221], v[220:221], v[150:151]
	v_pk_add_f32 v[2:3], v[2:3], v[4:5]
	v_cvt_pk_bf16_f32 v6, v218, v219
	v_cvt_pk_bf16_f32 v7, v220, v221
	v_add_f32_e32 v247, v2, v3
	v_lshlrev_b32_e32 v218, 16, v6
	v_mov_b32_dpp v166, v6 quad_perm:[1,0,3,2] row_mask:0xf bank_mask:0xf bound_ctrl:1
	v_and_b32_e32 v219, s21, v6
	v_mov_b32_dpp v167, v7 quad_perm:[1,0,3,2] row_mask:0xf bank_mask:0xf bound_ctrl:1
	v_lshlrev_b32_e32 v220, 16, v7
	v_and_b32_e32 v221, s21, v7
	v_perm_b32 v238, v166, v6, v125
	v_perm_b32 v239, v167, v7, v125
	global_store_dword v126, v238, s[18:19] offset:32
	global_store_dword v127, v239, s[18:19] offset:32
	v_fma_f32 v244, v218, v223, v219
	v_fma_f32 v245, v221, v224, v220
	v_fma_f32 v244, v244, v224, v220
	v_fma_f32 v245, v245, v223, v219
	v_fma_f32 v244, v244, v225, v221
	v_fma_f32 v245, v245, v222, v218
	ds_bpermute_b32 v240, v129, v247
	v_cndmask_b32_e64 v176, v245, v244, s[30:31]
	v_exp_f32_e32 v242, v247
	ds_bpermute_b32 v241, v129, v176
	s_waitcnt lgkmcnt(2)
	v_exp_f32_e32 v213, v210
	v_fma_f32 v215, v211, v212, v175
	v_add_f32_e32 v246, v246, v210
	v_fma_f32 v214, v175, v213, v211
	v_cndmask_b32_e64 v175, v215, v214, s[38:39]
	s_waitcnt lgkmcnt(0)
	v_exp_f32_e32 v243, v240
	v_fma_f32 v245, v241, v242, v176
	v_add_f32_e32 v247, v247, v240
	v_fma_f32 v244, v176, v243, v241
	v_cndmask_b32_e64 v176, v245, v244, s[40:41]
	ds_bpermute_b32 v240, v177, v247
	v_exp_f32_e32 v242, v247
	ds_bpermute_b32 v241, v177, v176
	s_waitcnt lgkmcnt(0)
	v_exp_f32_e32 v243, v240
	v_fma_f32 v245, v241, v242, v176
	v_add_f32_e32 v247, v247, v240
	v_fma_f32 v244, v176, v243, v241
	v_cndmask_b32_e64 v176, v245, v244, s[38:39]
	v_add_f32_e32 v178, v152, v153
	v_add_f32_e32 v179, v154, v155
	v_add_f32_e32 v180, v156, v157
	v_add_f32_e32 v181, v246, v247
	v_add_f32_e32 v178, v178, v179
	v_add_f32_e32 v180, v180, v181
	v_exp_f32_e32 v178, v178
	v_exp_f32_e32 v180, v180
	s_cmp_lg_u32 s10, 0
	s_cbranch_scc1 .Lrgx_bwd_np1
	v_exp_f32_e32 v184, v153
	v_exp_f32_e32 v185, v154
	v_exp_f32_e32 v186, v155
	v_exp_f32_e32 v222, v157
	v_exp_f32_e32 v223, v246
	v_exp_f32_e32 v224, v247
	v_fma_f32 v214, v169, v184, v170
	v_fma_f32 v215, v173, v222, v174
	v_fma_f32 v214, v214, v185, v171
	v_fma_f32 v215, v215, v223, v175
	v_fma_f32 v214, v214, v186, v172
	v_fma_f32 v215, v215, v224, v176
	s_branch .Lrgx_st_np1
